# epilogue peephole: 46 sites where four copies plus a packed multiply become two plain f32 multiplies (bit-identical)
# speedup vs baseline: 1.0044x; 1.0044x over previous
.LBB0_204:
	v_ashrrev_i32_e32 v0, 31, v202
	v_mul_lo_u32 v174, s57, v202
	v_mul_lo_u32 v0, s56, v0
	v_mad_u64_u32 v[176:177], s[10:11], s56, v202, 0
	v_add3_u32 v177, v177, v0, v174
	v_pk_mul_f32 v[174:175], v[128:129], s[8:9] op_sel_hi:[1,0]
	v_pk_mul_f32 v[204:205], v[126:127], s[8:9] op_sel_hi:[1,0]
	v_min_f32_e32 v174, 0x41e6d4ca, v174
	v_min_f32_e32 v203, 0x41e6d4ca, v204
	v_exp_f32_e32 v207, v203
	v_min_f32_e32 v203, 0x41e6d4ca, v205
	v_exp_f32_e32 v205, v174
	v_min_f32_e32 v174, 0x41e6d4ca, v175
	v_exp_f32_e32 v206, v203
	v_exp_f32_e32 v204, v174
	v_pk_add_f32 v[174:175], v[206:207], 1.0 op_sel_hi:[1,0]
	v_pk_add_f32 v[204:205], v[204:205], 1.0 op_sel_hi:[1,0]
	v_mul_f32_e32 v206, v175, v174
	v_mul_f32_e32 v207, v205, v204
	s_nop 0
	v_mul_f32_e32 v203, v206, v207
	v_rcp_f32_e32 v203, v203
	s_nop 0
	v_mul_f32_e32 v208, v207, v203
	v_mul_f32_e32 v206, v206, v203
	v_pk_mul_f32 v[174:175], v[174:175], v[208:209] op_sel_hi:[1,0]
	v_pk_mul_f32 v[204:205], v[204:205], v[206:207] op_sel_hi:[1,0]
	s_waitcnt vmcnt(0)
	v_cndmask_b32_e64 v207, v143, v127, s[42:43]
	v_cndmask_b32_e64 v206, v142, v126, s[42:43]
	v_pk_mul_f32 v[174:175], v[206:207], v[174:175]
	v_pk_mul_f32 v[206:207], v[122:123], s[8:9] op_sel_hi:[1,0]
	v_cndmask_b32_e64 v209, v145, v129, s[42:43]
	v_cndmask_b32_e64 v208, v144, v128, s[42:43]
	v_min_f32_e32 v203, 0x41e6d4ca, v206
	v_pk_mul_f32 v[208:209], v[208:209], v[204:205]
	v_pk_mul_f32 v[204:205], v[124:125], s[8:9] op_sel_hi:[1,0]
	v_exp_f32_e32 v211, v203
	v_min_f32_e32 v203, 0x41e6d4ca, v207
	v_exp_f32_e32 v210, v203
	v_min_f32_e32 v203, 0x41e6d4ca, v204
	v_exp_f32_e32 v207, v203
	v_min_f32_e32 v203, 0x41e6d4ca, v205
	v_exp_f32_e32 v206, v203
	v_pk_add_f32 v[204:205], v[210:211], 1.0 op_sel_hi:[1,0]
	v_pk_add_f32 v[206:207], v[206:207], 1.0 op_sel_hi:[1,0]
	v_mul_f32_e32 v210, v205, v204
	v_mul_f32_e32 v211, v207, v206
	s_nop 0
	v_mul_f32_e32 v203, v210, v211
	v_rcp_f32_e32 v203, v203
	s_nop 0
	v_mul_f32_e32 v212, v211, v203
	v_mul_f32_e32 v210, v210, v203
	v_pk_mul_f32 v[204:205], v[204:205], v[212:213] op_sel_hi:[1,0]
	v_pk_mul_f32 v[206:207], v[206:207], v[210:211] op_sel_hi:[1,0]
	v_cndmask_b32_e64 v211, v139, v123, s[42:43]
	v_cndmask_b32_e64 v210, v138, v122, s[42:43]
	v_cndmask_b32_e64 v213, v141, v125, s[42:43]
	v_cndmask_b32_e64 v212, v140, v124, s[42:43]
	v_pk_mul_f32 v[212:213], v[212:213], v[206:207]
	v_pk_mul_f32 v[206:207], v[210:211], v[204:205]
	v_cvt_pk_bf16_f32 v204, v174, v175
	v_cvt_pk_bf16_f32 v205, v208, v209
	v_lshl_add_u64 v[174:175], v[170:171], 1, s[86:87]
	v_lshlrev_b64 v[208:209], 1, v[176:177]
	v_cvt_pk_bf16_f32 v206, v206, v207
	v_cvt_pk_bf16_f32 v207, v212, v213
	v_lshl_add_u64 v[176:177], v[174:175], 0, v[208:209]
	global_store_dwordx4 v[176:177], v[204:207], off
	v_pk_mul_f32 v[176:177], v[120:121], s[8:9] op_sel_hi:[1,0]
	s_nop 0
	v_pk_mul_f32 v[204:205], v[118:119], s[8:9] op_sel_hi:[1,0]
	v_min_f32_e32 v176, 0x41e6d4ca, v176
	v_min_f32_e32 v203, 0x41e6d4ca, v204
	v_exp_f32_e32 v207, v203
	v_min_f32_e32 v203, 0x41e6d4ca, v205
	v_exp_f32_e32 v205, v176
	v_min_f32_e32 v176, 0x41e6d4ca, v177
	v_exp_f32_e32 v206, v203
	v_exp_f32_e32 v204, v176
	v_pk_add_f32 v[176:177], v[206:207], 1.0 op_sel_hi:[1,0]
	v_pk_add_f32 v[204:205], v[204:205], 1.0 op_sel_hi:[1,0]
	v_mul_f32_e32 v206, v177, v176
	v_mul_f32_e32 v207, v205, v204
	s_nop 0
	v_mul_f32_e32 v203, v206, v207
	v_rcp_f32_e32 v203, v203
	s_nop 0
	v_mul_f32_e32 v210, v207, v203
	v_mul_f32_e32 v206, v206, v203
	v_pk_mul_f32 v[176:177], v[176:177], v[210:211] op_sel_hi:[1,0]
	v_pk_mul_f32 v[204:205], v[204:205], v[206:207] op_sel_hi:[1,0]
	v_cndmask_b32_e64 v207, v135, v119, s[42:43]
	v_cndmask_b32_e64 v206, v134, v118, s[42:43]
	v_pk_mul_f32 v[176:177], v[206:207], v[176:177]
	v_pk_mul_f32 v[206:207], v[114:115], s[8:9] op_sel_hi:[1,0]
	v_cndmask_b32_e64 v211, v137, v121, s[42:43]
	v_cndmask_b32_e64 v210, v136, v120, s[42:43]
	v_min_f32_e32 v203, 0x41e6d4ca, v206
	v_pk_mul_f32 v[210:211], v[210:211], v[204:205]
	v_pk_mul_f32 v[204:205], v[116:117], s[8:9] op_sel_hi:[1,0]
	v_exp_f32_e32 v213, v203
	v_min_f32_e32 v203, 0x41e6d4ca, v207
	v_exp_f32_e32 v212, v203
	v_min_f32_e32 v203, 0x41e6d4ca, v204
	v_exp_f32_e32 v207, v203
	v_min_f32_e32 v203, 0x41e6d4ca, v205
	v_exp_f32_e32 v206, v203
	v_pk_add_f32 v[204:205], v[212:213], 1.0 op_sel_hi:[1,0]
	v_pk_add_f32 v[206:207], v[206:207], 1.0 op_sel_hi:[1,0]
	v_mul_f32_e32 v212, v205, v204
	v_mul_f32_e32 v213, v207, v206
	s_nop 0
	v_mul_f32_e32 v203, v212, v213
	v_rcp_f32_e32 v203, v203
	s_nop 0
	v_mul_f32_e32 v216, v213, v203
	v_mul_f32_e32 v212, v212, v203
	v_pk_mul_f32 v[204:205], v[204:205], v[216:217] op_sel_hi:[1,0]
	v_pk_mul_f32 v[206:207], v[206:207], v[212:213] op_sel_hi:[1,0]
	v_cndmask_b32_e64 v213, v131, v115, s[42:43]
	v_cndmask_b32_e64 v212, v130, v114, s[42:43]
	v_cndmask_b32_e64 v217, v133, v117, s[42:43]
	v_cndmask_b32_e64 v216, v132, v116, s[42:43]
	v_pk_mul_f32 v[216:217], v[216:217], v[206:207]
	v_pk_mul_f32 v[206:207], v[212:213], v[204:205]
	v_cvt_pk_bf16_f32 v204, v176, v177
	v_lshl_add_u64 v[176:177], v[172:173], 1, s[86:87]
	v_cvt_pk_bf16_f32 v205, v210, v211
	v_cvt_pk_bf16_f32 v206, v206, v207
	v_cvt_pk_bf16_f32 v207, v216, v217
	v_lshl_add_u64 v[208:209], v[176:177], 0, v[208:209]
	global_store_dwordx4 v[208:209], v[204:207], off
	v_or_b32_e32 v203, 16, v202
	v_mad_u64_u32 v[208:209], s[10:11], s56, v203, 0
	v_pk_mul_f32 v[206:207], v[110:111], s[8:9] op_sel_hi:[1,0]
	v_mul_lo_u32 v204, s57, v203
	v_min_f32_e32 v203, 0x41e6d4ca, v206
	v_add3_u32 v209, v209, v0, v204
	v_pk_mul_f32 v[204:205], v[112:113], s[8:9] op_sel_hi:[1,0]
	v_exp_f32_e32 v211, v203
	v_min_f32_e32 v203, 0x41e6d4ca, v207
	v_exp_f32_e32 v210, v203
	v_min_f32_e32 v203, 0x41e6d4ca, v204
	v_exp_f32_e32 v207, v203
	v_min_f32_e32 v203, 0x41e6d4ca, v205
	v_exp_f32_e32 v206, v203
	v_pk_add_f32 v[204:205], v[210:211], 1.0 op_sel_hi:[1,0]
	v_lshlrev_b64 v[208:209], 1, v[208:209]
	v_pk_add_f32 v[206:207], v[206:207], 1.0 op_sel_hi:[1,0]
	v_mul_f32_e32 v210, v205, v204
	v_mul_f32_e32 v211, v207, v206
	s_nop 0
	v_mul_f32_e32 v203, v210, v211
	v_rcp_f32_e32 v203, v203
	s_nop 0
	v_mul_f32_e32 v212, v211, v203
	v_mul_f32_e32 v210, v210, v203
	v_pk_mul_f32 v[204:205], v[204:205], v[212:213] op_sel_hi:[1,0]
	v_pk_mul_f32 v[206:207], v[206:207], v[210:211] op_sel_hi:[1,0]
	v_cndmask_b32_e64 v213, v145, v113, s[42:43]
	v_cndmask_b32_e64 v212, v144, v112, s[42:43]
	v_pk_mul_f32 v[206:207], v[212:213], v[206:207]
	v_pk_mul_f32 v[212:213], v[106:107], s[8:9] op_sel_hi:[1,0]
	v_cndmask_b32_e64 v211, v143, v111, s[42:43]
	v_cndmask_b32_e64 v210, v142, v110, s[42:43]
	v_min_f32_e32 v203, 0x41e6d4ca, v212
	v_pk_mul_f32 v[204:205], v[210:211], v[204:205]
	v_pk_mul_f32 v[210:211], v[108:109], s[8:9] op_sel_hi:[1,0]
	v_exp_f32_e32 v217, v203
	v_min_f32_e32 v203, 0x41e6d4ca, v213
	v_exp_f32_e32 v216, v203
	v_min_f32_e32 v203, 0x41e6d4ca, v210
	v_exp_f32_e32 v213, v203
	v_min_f32_e32 v203, 0x41e6d4ca, v211
	v_exp_f32_e32 v212, v203
	v_pk_add_f32 v[210:211], v[216:217], 1.0 op_sel_hi:[1,0]
	v_cvt_pk_bf16_f32 v204, v204, v205
	v_pk_add_f32 v[212:213], v[212:213], 1.0 op_sel_hi:[1,0]
	v_mul_f32_e32 v216, v211, v210
	v_mul_f32_e32 v217, v213, v212
	v_cvt_pk_bf16_f32 v205, v206, v207
	v_mul_f32_e32 v203, v216, v217
	v_rcp_f32_e32 v203, v203
	s_nop 0
	v_mul_f32_e32 v218, v217, v203
	v_mul_f32_e32 v216, v216, v203
	v_pk_mul_f32 v[210:211], v[210:211], v[218:219] op_sel_hi:[1,0]
	v_pk_mul_f32 v[212:213], v[212:213], v[216:217] op_sel_hi:[1,0]
	v_cndmask_b32_e64 v217, v139, v107, s[42:43]
	v_cndmask_b32_e64 v216, v138, v106, s[42:43]
	v_cndmask_b32_e64 v219, v141, v109, s[42:43]
	v_cndmask_b32_e64 v218, v140, v108, s[42:43]
	v_pk_mul_f32 v[212:213], v[218:219], v[212:213]
	v_pk_mul_f32 v[210:211], v[216:217], v[210:211]
	v_cvt_pk_bf16_f32 v207, v212, v213
	v_cvt_pk_bf16_f32 v206, v210, v211
	v_lshl_add_u64 v[210:211], v[174:175], 0, v[208:209]
	global_store_dwordx4 v[210:211], v[204:207], off
	v_lshl_add_u64 v[208:209], v[176:177], 0, v[208:209]
	s_nop 0
	v_pk_mul_f32 v[206:207], v[102:103], s[8:9] op_sel_hi:[1,0]
	v_pk_mul_f32 v[204:205], v[104:105], s[8:9] op_sel_hi:[1,0]
	v_min_f32_e32 v203, 0x41e6d4ca, v206
	v_exp_f32_e32 v211, v203
	v_min_f32_e32 v203, 0x41e6d4ca, v207
	v_exp_f32_e32 v210, v203
	v_min_f32_e32 v203, 0x41e6d4ca, v204
	v_exp_f32_e32 v207, v203
	v_min_f32_e32 v203, 0x41e6d4ca, v205
	v_exp_f32_e32 v206, v203
	v_pk_add_f32 v[204:205], v[210:211], 1.0 op_sel_hi:[1,0]
	v_pk_add_f32 v[206:207], v[206:207], 1.0 op_sel_hi:[1,0]
	v_mul_f32_e32 v210, v205, v204
	v_mul_f32_e32 v211, v207, v206
	s_nop 0
	v_mul_f32_e32 v203, v210, v211
	v_rcp_f32_e32 v203, v203
	s_nop 0
	v_mul_f32_e32 v212, v211, v203
	v_mul_f32_e32 v210, v210, v203
	v_pk_mul_f32 v[204:205], v[204:205], v[212:213] op_sel_hi:[1,0]
	v_pk_mul_f32 v[206:207], v[206:207], v[210:211] op_sel_hi:[1,0]
	v_cndmask_b32_e64 v213, v137, v105, s[42:43]
	v_cndmask_b32_e64 v212, v136, v104, s[42:43]
	v_pk_mul_f32 v[206:207], v[212:213], v[206:207]
	v_pk_mul_f32 v[212:213], v[98:99], s[8:9] op_sel_hi:[1,0]
	v_cndmask_b32_e64 v211, v135, v103, s[42:43]
	v_cndmask_b32_e64 v210, v134, v102, s[42:43]
	v_min_f32_e32 v203, 0x41e6d4ca, v212
	v_pk_mul_f32 v[204:205], v[210:211], v[204:205]
	v_pk_mul_f32 v[210:211], v[100:101], s[8:9] op_sel_hi:[1,0]
	v_exp_f32_e32 v217, v203
	v_min_f32_e32 v203, 0x41e6d4ca, v213
	v_exp_f32_e32 v216, v203
	v_min_f32_e32 v203, 0x41e6d4ca, v210
	v_exp_f32_e32 v213, v203
	v_min_f32_e32 v203, 0x41e6d4ca, v211
	v_exp_f32_e32 v212, v203
	v_pk_add_f32 v[210:211], v[216:217], 1.0 op_sel_hi:[1,0]
	v_cvt_pk_bf16_f32 v204, v204, v205
	v_pk_add_f32 v[212:213], v[212:213], 1.0 op_sel_hi:[1,0]
	v_mul_f32_e32 v216, v211, v210
	v_mul_f32_e32 v217, v213, v212
	v_cvt_pk_bf16_f32 v205, v206, v207
	v_mul_f32_e32 v203, v216, v217
	v_rcp_f32_e32 v203, v203
	s_nop 0
	v_mul_f32_e32 v218, v217, v203
	v_mul_f32_e32 v216, v216, v203
	v_pk_mul_f32 v[210:211], v[210:211], v[218:219] op_sel_hi:[1,0]
	v_pk_mul_f32 v[212:213], v[212:213], v[216:217] op_sel_hi:[1,0]
	v_cndmask_b32_e64 v217, v131, v99, s[42:43]
	v_cndmask_b32_e64 v216, v130, v98, s[42:43]
	v_cndmask_b32_e64 v219, v133, v101, s[42:43]
	v_cndmask_b32_e64 v218, v132, v100, s[42:43]
	v_pk_mul_f32 v[212:213], v[218:219], v[212:213]
	v_pk_mul_f32 v[210:211], v[216:217], v[210:211]
	v_cvt_pk_bf16_f32 v207, v212, v213
	v_cvt_pk_bf16_f32 v206, v210, v211
	global_store_dwordx4 v[208:209], v[204:207], off
	v_or_b32_e32 v203, 32, v202
	v_mad_u64_u32 v[208:209], s[10:11], s56, v203, 0
	v_pk_mul_f32 v[206:207], v[94:95], s[8:9] op_sel_hi:[1,0]
	v_mul_lo_u32 v204, s57, v203
	v_min_f32_e32 v203, 0x41e6d4ca, v206
	v_add3_u32 v209, v209, v0, v204
	v_pk_mul_f32 v[204:205], v[96:97], s[8:9] op_sel_hi:[1,0]
	v_exp_f32_e32 v211, v203
	v_min_f32_e32 v203, 0x41e6d4ca, v207
	v_exp_f32_e32 v210, v203
	v_min_f32_e32 v203, 0x41e6d4ca, v204
	v_exp_f32_e32 v207, v203
	v_min_f32_e32 v203, 0x41e6d4ca, v205
	v_exp_f32_e32 v206, v203
	v_pk_add_f32 v[204:205], v[210:211], 1.0 op_sel_hi:[1,0]
	v_lshlrev_b64 v[208:209], 1, v[208:209]
	v_pk_add_f32 v[206:207], v[206:207], 1.0 op_sel_hi:[1,0]
	v_mul_f32_e32 v210, v205, v204
	v_mul_f32_e32 v211, v207, v206
	s_nop 0
	v_mul_f32_e32 v203, v210, v211
	v_rcp_f32_e32 v203, v203
	s_nop 0
	v_mul_f32_e32 v212, v211, v203
	v_mul_f32_e32 v210, v210, v203
	v_pk_mul_f32 v[204:205], v[204:205], v[212:213] op_sel_hi:[1,0]
	v_pk_mul_f32 v[206:207], v[206:207], v[210:211] op_sel_hi:[1,0]
	v_cndmask_b32_e64 v213, v145, v97, s[42:43]
	v_cndmask_b32_e64 v212, v144, v96, s[42:43]
	v_pk_mul_f32 v[206:207], v[212:213], v[206:207]
	v_pk_mul_f32 v[212:213], v[90:91], s[8:9] op_sel_hi:[1,0]
	v_cndmask_b32_e64 v211, v143, v95, s[42:43]
	v_cndmask_b32_e64 v210, v142, v94, s[42:43]
	v_min_f32_e32 v203, 0x41e6d4ca, v212
	v_pk_mul_f32 v[204:205], v[210:211], v[204:205]
	v_pk_mul_f32 v[210:211], v[92:93], s[8:9] op_sel_hi:[1,0]
	v_exp_f32_e32 v217, v203
	v_min_f32_e32 v203, 0x41e6d4ca, v213
	v_exp_f32_e32 v216, v203
	v_min_f32_e32 v203, 0x41e6d4ca, v210
	v_exp_f32_e32 v213, v203
	v_min_f32_e32 v203, 0x41e6d4ca, v211
	v_exp_f32_e32 v212, v203
	v_pk_add_f32 v[210:211], v[216:217], 1.0 op_sel_hi:[1,0]
	v_cvt_pk_bf16_f32 v204, v204, v205
	v_pk_add_f32 v[212:213], v[212:213], 1.0 op_sel_hi:[1,0]
	v_mul_f32_e32 v216, v211, v210
	v_mul_f32_e32 v217, v213, v212
	v_cvt_pk_bf16_f32 v205, v206, v207
	v_mul_f32_e32 v203, v216, v217
	v_rcp_f32_e32 v203, v203
	s_nop 0
	v_mul_f32_e32 v218, v217, v203
	v_mul_f32_e32 v216, v216, v203
	v_pk_mul_f32 v[210:211], v[210:211], v[218:219] op_sel_hi:[1,0]
	v_pk_mul_f32 v[212:213], v[212:213], v[216:217] op_sel_hi:[1,0]
	v_cndmask_b32_e64 v217, v139, v91, s[42:43]
	v_cndmask_b32_e64 v216, v138, v90, s[42:43]
	v_cndmask_b32_e64 v219, v141, v93, s[42:43]
	v_cndmask_b32_e64 v218, v140, v92, s[42:43]
	v_pk_mul_f32 v[212:213], v[218:219], v[212:213]
	v_pk_mul_f32 v[210:211], v[216:217], v[210:211]
	v_cvt_pk_bf16_f32 v207, v212, v213
	v_cvt_pk_bf16_f32 v206, v210, v211
	v_lshl_add_u64 v[210:211], v[174:175], 0, v[208:209]
	global_store_dwordx4 v[210:211], v[204:207], off
	v_lshl_add_u64 v[208:209], v[176:177], 0, v[208:209]
	s_nop 0
	v_pk_mul_f32 v[206:207], v[86:87], s[8:9] op_sel_hi:[1,0]
	v_pk_mul_f32 v[204:205], v[88:89], s[8:9] op_sel_hi:[1,0]
	v_min_f32_e32 v203, 0x41e6d4ca, v206
	v_exp_f32_e32 v211, v203
	v_min_f32_e32 v203, 0x41e6d4ca, v207
	v_exp_f32_e32 v210, v203
	v_min_f32_e32 v203, 0x41e6d4ca, v204
	v_exp_f32_e32 v207, v203
	v_min_f32_e32 v203, 0x41e6d4ca, v205
	v_exp_f32_e32 v206, v203
	v_pk_add_f32 v[204:205], v[210:211], 1.0 op_sel_hi:[1,0]
	v_pk_add_f32 v[206:207], v[206:207], 1.0 op_sel_hi:[1,0]
	v_mul_f32_e32 v210, v205, v204
	v_mul_f32_e32 v211, v207, v206
	s_nop 0
	v_mul_f32_e32 v203, v210, v211
	v_rcp_f32_e32 v203, v203
	s_nop 0
	v_mul_f32_e32 v212, v211, v203
	v_mul_f32_e32 v210, v210, v203
	v_pk_mul_f32 v[204:205], v[204:205], v[212:213] op_sel_hi:[1,0]
	v_pk_mul_f32 v[206:207], v[206:207], v[210:211] op_sel_hi:[1,0]
	v_cndmask_b32_e64 v213, v137, v89, s[42:43]
	v_cndmask_b32_e64 v212, v136, v88, s[42:43]
	v_pk_mul_f32 v[206:207], v[212:213], v[206:207]
	v_pk_mul_f32 v[212:213], v[82:83], s[8:9] op_sel_hi:[1,0]
	v_cndmask_b32_e64 v211, v135, v87, s[42:43]
	v_cndmask_b32_e64 v210, v134, v86, s[42:43]
	v_min_f32_e32 v203, 0x41e6d4ca, v212
	v_pk_mul_f32 v[204:205], v[210:211], v[204:205]
	v_pk_mul_f32 v[210:211], v[84:85], s[8:9] op_sel_hi:[1,0]
	v_exp_f32_e32 v217, v203
	v_min_f32_e32 v203, 0x41e6d4ca, v213
	v_exp_f32_e32 v216, v203
	v_min_f32_e32 v203, 0x41e6d4ca, v210
	v_exp_f32_e32 v213, v203
	v_min_f32_e32 v203, 0x41e6d4ca, v211
	v_exp_f32_e32 v212, v203
	v_pk_add_f32 v[210:211], v[216:217], 1.0 op_sel_hi:[1,0]
	v_cvt_pk_bf16_f32 v204, v204, v205
	v_pk_add_f32 v[212:213], v[212:213], 1.0 op_sel_hi:[1,0]
	v_mul_f32_e32 v216, v211, v210
	v_mul_f32_e32 v217, v213, v212
	v_cvt_pk_bf16_f32 v205, v206, v207
	v_mul_f32_e32 v203, v216, v217
	v_rcp_f32_e32 v203, v203
	s_nop 0
	v_mul_f32_e32 v218, v217, v203
	v_mul_f32_e32 v216, v216, v203
	v_pk_mul_f32 v[210:211], v[210:211], v[218:219] op_sel_hi:[1,0]
	v_pk_mul_f32 v[212:213], v[212:213], v[216:217] op_sel_hi:[1,0]
	v_cndmask_b32_e64 v217, v131, v83, s[42:43]
	v_cndmask_b32_e64 v216, v130, v82, s[42:43]
	v_cndmask_b32_e64 v219, v133, v85, s[42:43]
	v_cndmask_b32_e64 v218, v132, v84, s[42:43]
	v_pk_mul_f32 v[212:213], v[218:219], v[212:213]
	v_pk_mul_f32 v[210:211], v[216:217], v[210:211]
	v_cvt_pk_bf16_f32 v207, v212, v213
	v_cvt_pk_bf16_f32 v206, v210, v211
	v_or_b32_e32 v203, 48, v202
	global_store_dwordx4 v[208:209], v[204:207], off
	v_mad_u64_u32 v[208:209], s[10:11], s56, v203, 0
	s_nop 0
	v_mul_lo_u32 v204, s57, v203
	v_pk_mul_f32 v[206:207], v[78:79], s[8:9] op_sel_hi:[1,0]
	v_add3_u32 v209, v209, v0, v204
	v_min_f32_e32 v0, 0x41e6d4ca, v206
	v_pk_mul_f32 v[204:205], v[80:81], s[8:9] op_sel_hi:[1,0]
	v_exp_f32_e32 v211, v0
	v_min_f32_e32 v0, 0x41e6d4ca, v207
	v_exp_f32_e32 v210, v0
	v_min_f32_e32 v0, 0x41e6d4ca, v204
	v_exp_f32_e32 v207, v0
	v_min_f32_e32 v0, 0x41e6d4ca, v205
	v_exp_f32_e32 v206, v0
	v_pk_add_f32 v[204:205], v[210:211], 1.0 op_sel_hi:[1,0]
	v_lshlrev_b64 v[208:209], 1, v[208:209]
	v_pk_add_f32 v[206:207], v[206:207], 1.0 op_sel_hi:[1,0]
	v_mul_f32_e32 v210, v205, v204
	v_mul_f32_e32 v211, v207, v206
	v_cndmask_b32_e64 v213, v145, v81, s[42:43]
	v_mul_f32_e32 v0, v210, v211
	v_rcp_f32_e32 v203, v0
	v_cndmask_b32_e64 v212, v144, v80, s[42:43]
	v_mul_f32_e32 v210, v210, v203
	v_pk_mul_f32 v[206:207], v[206:207], v[210:211] op_sel_hi:[1,0]
	v_mul_f32_e32 v0, v211, v203
	v_pk_mul_f32 v[206:207], v[212:213], v[206:207]
	v_pk_mul_f32 v[212:213], v[74:75], s[8:9] op_sel_hi:[1,0]
	v_pk_mul_f32 v[204:205], v[204:205], v[0:1] op_sel_hi:[1,0]
	v_cndmask_b32_e64 v211, v143, v79, s[42:43]
	v_cndmask_b32_e64 v210, v142, v78, s[42:43]
	v_min_f32_e32 v0, 0x41e6d4ca, v212
	v_pk_mul_f32 v[204:205], v[210:211], v[204:205]
	v_pk_mul_f32 v[210:211], v[76:77], s[8:9] op_sel_hi:[1,0]
	v_exp_f32_e32 v217, v0
	v_min_f32_e32 v0, 0x41e6d4ca, v213
	v_exp_f32_e32 v216, v0
	v_min_f32_e32 v0, 0x41e6d4ca, v210
	v_exp_f32_e32 v213, v0
	v_min_f32_e32 v0, 0x41e6d4ca, v211
	v_exp_f32_e32 v212, v0
	v_pk_add_f32 v[210:211], v[216:217], 1.0 op_sel_hi:[1,0]
	v_cvt_pk_bf16_f32 v204, v204, v205
	v_pk_add_f32 v[212:213], v[212:213], 1.0 op_sel_hi:[1,0]
	v_mul_f32_e32 v216, v211, v210
	v_mul_f32_e32 v217, v213, v212
	v_cndmask_b32_e64 v219, v141, v77, s[42:43]
	v_mul_f32_e32 v0, v216, v217
	v_rcp_f32_e32 v203, v0
	v_cndmask_b32_e64 v218, v140, v76, s[42:43]
	v_cvt_pk_bf16_f32 v205, v206, v207
	v_mul_f32_e32 v0, v217, v203
	v_mul_f32_e32 v216, v216, v203
	v_pk_mul_f32 v[210:211], v[210:211], v[0:1] op_sel_hi:[1,0]
	v_pk_mul_f32 v[212:213], v[212:213], v[216:217] op_sel_hi:[1,0]
	v_cndmask_b32_e64 v217, v139, v75, s[42:43]
	v_cndmask_b32_e64 v216, v138, v74, s[42:43]
	v_pk_mul_f32 v[212:213], v[218:219], v[212:213]
	v_pk_mul_f32 v[210:211], v[216:217], v[210:211]
	v_cvt_pk_bf16_f32 v207, v212, v213
	v_cvt_pk_bf16_f32 v206, v210, v211
	v_lshl_add_u64 v[210:211], v[174:175], 0, v[208:209]
	global_store_dwordx4 v[210:211], v[204:207], off
	v_lshl_add_u64 v[208:209], v[176:177], 0, v[208:209]
	s_nop 0
	v_pk_mul_f32 v[206:207], v[70:71], s[8:9] op_sel_hi:[1,0]
	v_pk_mul_f32 v[204:205], v[72:73], s[8:9] op_sel_hi:[1,0]
	v_min_f32_e32 v0, 0x41e6d4ca, v206
	v_exp_f32_e32 v211, v0
	v_min_f32_e32 v0, 0x41e6d4ca, v207
	v_exp_f32_e32 v210, v0
	v_min_f32_e32 v0, 0x41e6d4ca, v204
	v_exp_f32_e32 v207, v0
	v_min_f32_e32 v0, 0x41e6d4ca, v205
	v_exp_f32_e32 v206, v0
	v_pk_add_f32 v[204:205], v[210:211], 1.0 op_sel_hi:[1,0]
	v_pk_add_f32 v[206:207], v[206:207], 1.0 op_sel_hi:[1,0]
	v_mul_f32_e32 v210, v205, v204
	v_mul_f32_e32 v211, v207, v206
	v_cndmask_b32_e64 v213, v137, v73, s[42:43]
	v_mul_f32_e32 v0, v210, v211
	v_rcp_f32_e32 v203, v0
	v_cndmask_b32_e64 v212, v136, v72, s[42:43]
	v_mul_f32_e32 v210, v210, v203
	v_pk_mul_f32 v[206:207], v[206:207], v[210:211] op_sel_hi:[1,0]
	v_mul_f32_e32 v0, v211, v203
	v_pk_mul_f32 v[206:207], v[212:213], v[206:207]
	v_pk_mul_f32 v[212:213], v[66:67], s[8:9] op_sel_hi:[1,0]
	v_pk_mul_f32 v[204:205], v[204:205], v[0:1] op_sel_hi:[1,0]
	v_cndmask_b32_e64 v211, v135, v71, s[42:43]
	v_cndmask_b32_e64 v210, v134, v70, s[42:43]
	v_min_f32_e32 v0, 0x41e6d4ca, v212
	v_pk_mul_f32 v[204:205], v[210:211], v[204:205]
	v_pk_mul_f32 v[210:211], v[68:69], s[8:9] op_sel_hi:[1,0]
	v_exp_f32_e32 v217, v0
	v_min_f32_e32 v0, 0x41e6d4ca, v213
	v_exp_f32_e32 v216, v0
	v_min_f32_e32 v0, 0x41e6d4ca, v210
	v_exp_f32_e32 v213, v0
	v_min_f32_e32 v0, 0x41e6d4ca, v211
	v_exp_f32_e32 v212, v0
	v_pk_add_f32 v[210:211], v[216:217], 1.0 op_sel_hi:[1,0]
	v_cvt_pk_bf16_f32 v204, v204, v205
	v_pk_add_f32 v[212:213], v[212:213], 1.0 op_sel_hi:[1,0]
	v_mul_f32_e32 v216, v211, v210
	v_mul_f32_e32 v217, v213, v212
	v_cndmask_b32_e64 v219, v133, v69, s[42:43]
	v_mul_f32_e32 v0, v216, v217
	v_rcp_f32_e32 v203, v0
	v_cndmask_b32_e64 v218, v132, v68, s[42:43]
	v_cvt_pk_bf16_f32 v205, v206, v207
	v_mul_f32_e32 v0, v217, v203
	v_mul_f32_e32 v216, v216, v203
	v_pk_mul_f32 v[210:211], v[210:211], v[0:1] op_sel_hi:[1,0]
	v_pk_mul_f32 v[212:213], v[212:213], v[216:217] op_sel_hi:[1,0]
	v_cndmask_b32_e64 v217, v131, v67, s[42:43]
	v_cndmask_b32_e64 v216, v130, v66, s[42:43]
	v_pk_mul_f32 v[212:213], v[218:219], v[212:213]
	v_pk_mul_f32 v[210:211], v[216:217], v[210:211]
	v_cvt_pk_bf16_f32 v207, v212, v213
	v_cvt_pk_bf16_f32 v206, v210, v211
	v_add_u32_e32 v0, 0x80, v202
	global_store_dwordx4 v[208:209], v[204:207], off
	v_ashrrev_i32_e32 v203, 31, v0
	v_mul_lo_u32 v203, s56, v203
	v_pk_mul_f32 v[206:207], v[62:63], s[8:9] op_sel_hi:[1,0]
	v_mul_lo_u32 v204, s57, v0
	v_mad_u64_u32 v[208:209], s[10:11], s56, v0, 0
	v_min_f32_e32 v0, 0x41e6d4ca, v206
	v_add3_u32 v209, v209, v203, v204
	v_pk_mul_f32 v[204:205], v[64:65], s[8:9] op_sel_hi:[1,0]
	v_exp_f32_e32 v211, v0
	v_min_f32_e32 v0, 0x41e6d4ca, v207
	v_exp_f32_e32 v210, v0
	v_min_f32_e32 v0, 0x41e6d4ca, v204
	v_exp_f32_e32 v207, v0
	v_min_f32_e32 v0, 0x41e6d4ca, v205
	v_exp_f32_e32 v206, v0
	v_pk_add_f32 v[204:205], v[210:211], 1.0 op_sel_hi:[1,0]
	v_lshlrev_b64 v[208:209], 1, v[208:209]
	v_pk_add_f32 v[206:207], v[206:207], 1.0 op_sel_hi:[1,0]
	v_mul_f32_e32 v210, v205, v204
	v_mul_f32_e32 v211, v207, v206
	v_cndmask_b32_e64 v213, v145, v65, s[42:43]
	v_mul_f32_e32 v0, v210, v211
	v_rcp_f32_e32 v203, v0
	v_cndmask_b32_e64 v212, v144, v64, s[42:43]
	v_mul_f32_e32 v210, v210, v203
	v_pk_mul_f32 v[206:207], v[206:207], v[210:211] op_sel_hi:[1,0]
	v_mul_f32_e32 v0, v211, v203
	v_pk_mul_f32 v[206:207], v[212:213], v[206:207]
	v_pk_mul_f32 v[212:213], v[58:59], s[8:9] op_sel_hi:[1,0]
	v_pk_mul_f32 v[204:205], v[204:205], v[0:1] op_sel_hi:[1,0]
	v_cndmask_b32_e64 v211, v143, v63, s[42:43]
	v_cndmask_b32_e64 v210, v142, v62, s[42:43]
	v_min_f32_e32 v0, 0x41e6d4ca, v212
	v_pk_mul_f32 v[204:205], v[210:211], v[204:205]
	v_pk_mul_f32 v[210:211], v[60:61], s[8:9] op_sel_hi:[1,0]
	v_exp_f32_e32 v217, v0
	v_min_f32_e32 v0, 0x41e6d4ca, v213
	v_exp_f32_e32 v216, v0
	v_min_f32_e32 v0, 0x41e6d4ca, v210
	v_exp_f32_e32 v213, v0
	v_min_f32_e32 v0, 0x41e6d4ca, v211
	v_exp_f32_e32 v212, v0
	v_pk_add_f32 v[210:211], v[216:217], 1.0 op_sel_hi:[1,0]
	v_cvt_pk_bf16_f32 v204, v204, v205
	v_pk_add_f32 v[212:213], v[212:213], 1.0 op_sel_hi:[1,0]
	v_mul_f32_e32 v216, v211, v210
	v_mul_f32_e32 v217, v213, v212
	v_cndmask_b32_e64 v219, v141, v61, s[42:43]
	v_mul_f32_e32 v0, v216, v217
	v_rcp_f32_e32 v203, v0
	v_cndmask_b32_e64 v218, v140, v60, s[42:43]
	v_cvt_pk_bf16_f32 v205, v206, v207
	v_mul_f32_e32 v0, v217, v203
	v_mul_f32_e32 v216, v216, v203
	v_pk_mul_f32 v[210:211], v[210:211], v[0:1] op_sel_hi:[1,0]
	v_pk_mul_f32 v[212:213], v[212:213], v[216:217] op_sel_hi:[1,0]
	v_cndmask_b32_e64 v217, v139, v59, s[42:43]
	v_cndmask_b32_e64 v216, v138, v58, s[42:43]
	v_pk_mul_f32 v[212:213], v[218:219], v[212:213]
	v_pk_mul_f32 v[210:211], v[216:217], v[210:211]
	v_cvt_pk_bf16_f32 v207, v212, v213
	v_cvt_pk_bf16_f32 v206, v210, v211
	v_lshl_add_u64 v[210:211], v[174:175], 0, v[208:209]
	global_store_dwordx4 v[210:211], v[204:207], off
	v_lshl_add_u64 v[208:209], v[176:177], 0, v[208:209]
	s_nop 0
	v_pk_mul_f32 v[206:207], v[54:55], s[8:9] op_sel_hi:[1,0]
	v_pk_mul_f32 v[204:205], v[56:57], s[8:9] op_sel_hi:[1,0]
	v_min_f32_e32 v0, 0x41e6d4ca, v206
	v_exp_f32_e32 v211, v0
	v_min_f32_e32 v0, 0x41e6d4ca, v207
	v_exp_f32_e32 v210, v0
	v_min_f32_e32 v0, 0x41e6d4ca, v204
	v_exp_f32_e32 v207, v0
	v_min_f32_e32 v0, 0x41e6d4ca, v205
	v_exp_f32_e32 v206, v0
	v_pk_add_f32 v[204:205], v[210:211], 1.0 op_sel_hi:[1,0]
	v_pk_add_f32 v[206:207], v[206:207], 1.0 op_sel_hi:[1,0]
	v_mul_f32_e32 v210, v205, v204
	v_mul_f32_e32 v211, v207, v206
	v_cndmask_b32_e64 v213, v137, v57, s[42:43]
	v_mul_f32_e32 v0, v210, v211
	v_rcp_f32_e32 v203, v0
	v_cndmask_b32_e64 v212, v136, v56, s[42:43]
	v_mul_f32_e32 v210, v210, v203
	v_pk_mul_f32 v[206:207], v[206:207], v[210:211] op_sel_hi:[1,0]
	v_mul_f32_e32 v0, v211, v203
	v_pk_mul_f32 v[206:207], v[212:213], v[206:207]
	v_pk_mul_f32 v[212:213], v[50:51], s[8:9] op_sel_hi:[1,0]
	v_pk_mul_f32 v[204:205], v[204:205], v[0:1] op_sel_hi:[1,0]
	v_cndmask_b32_e64 v211, v135, v55, s[42:43]
	v_cndmask_b32_e64 v210, v134, v54, s[42:43]
	v_min_f32_e32 v0, 0x41e6d4ca, v212
	v_pk_mul_f32 v[204:205], v[210:211], v[204:205]
	v_pk_mul_f32 v[210:211], v[52:53], s[8:9] op_sel_hi:[1,0]
	v_exp_f32_e32 v217, v0
	v_min_f32_e32 v0, 0x41e6d4ca, v213
	v_exp_f32_e32 v216, v0
	v_min_f32_e32 v0, 0x41e6d4ca, v210
	v_exp_f32_e32 v213, v0
	v_min_f32_e32 v0, 0x41e6d4ca, v211
	v_exp_f32_e32 v212, v0
	v_pk_add_f32 v[210:211], v[216:217], 1.0 op_sel_hi:[1,0]
	v_cvt_pk_bf16_f32 v204, v204, v205
	v_pk_add_f32 v[212:213], v[212:213], 1.0 op_sel_hi:[1,0]
	v_mul_f32_e32 v216, v211, v210
	v_mul_f32_e32 v217, v213, v212
	v_cndmask_b32_e64 v219, v133, v53, s[42:43]
	v_mul_f32_e32 v0, v216, v217
	v_rcp_f32_e32 v203, v0
	v_cndmask_b32_e64 v218, v132, v52, s[42:43]
	v_cvt_pk_bf16_f32 v205, v206, v207
	v_mul_f32_e32 v0, v217, v203
	v_mul_f32_e32 v216, v216, v203
	v_pk_mul_f32 v[210:211], v[210:211], v[0:1] op_sel_hi:[1,0]
	v_pk_mul_f32 v[212:213], v[212:213], v[216:217] op_sel_hi:[1,0]
	v_cndmask_b32_e64 v217, v131, v51, s[42:43]
	v_cndmask_b32_e64 v216, v130, v50, s[42:43]
	v_pk_mul_f32 v[212:213], v[218:219], v[212:213]
	v_pk_mul_f32 v[210:211], v[216:217], v[210:211]
	v_cvt_pk_bf16_f32 v207, v212, v213
	v_cvt_pk_bf16_f32 v206, v210, v211
	v_add_u32_e32 v0, 0x90, v202
	global_store_dwordx4 v[208:209], v[204:207], off
	v_ashrrev_i32_e32 v203, 31, v0
	v_mul_lo_u32 v203, s56, v203
	v_pk_mul_f32 v[206:207], v[46:47], s[8:9] op_sel_hi:[1,0]
	v_mul_lo_u32 v204, s57, v0
	v_mad_u64_u32 v[208:209], s[10:11], s56, v0, 0
	v_min_f32_e32 v0, 0x41e6d4ca, v206
	v_add3_u32 v209, v209, v203, v204
	v_pk_mul_f32 v[204:205], v[48:49], s[8:9] op_sel_hi:[1,0]
	v_exp_f32_e32 v211, v0
	v_min_f32_e32 v0, 0x41e6d4ca, v207
	v_exp_f32_e32 v210, v0
	v_min_f32_e32 v0, 0x41e6d4ca, v204
	v_exp_f32_e32 v207, v0
	v_min_f32_e32 v0, 0x41e6d4ca, v205
	v_exp_f32_e32 v206, v0
	v_pk_add_f32 v[204:205], v[210:211], 1.0 op_sel_hi:[1,0]
	v_lshlrev_b64 v[208:209], 1, v[208:209]
	v_pk_add_f32 v[206:207], v[206:207], 1.0 op_sel_hi:[1,0]
	v_mul_f32_e32 v210, v205, v204
	v_mul_f32_e32 v211, v207, v206
	v_cndmask_b32_e64 v213, v145, v49, s[42:43]
	v_mul_f32_e32 v0, v210, v211
	v_rcp_f32_e32 v203, v0
	v_cndmask_b32_e64 v212, v144, v48, s[42:43]
	v_mul_f32_e32 v210, v210, v203
	v_pk_mul_f32 v[206:207], v[206:207], v[210:211] op_sel_hi:[1,0]
	v_mul_f32_e32 v0, v211, v203
	v_pk_mul_f32 v[206:207], v[212:213], v[206:207]
	v_pk_mul_f32 v[212:213], v[42:43], s[8:9] op_sel_hi:[1,0]
	v_pk_mul_f32 v[204:205], v[204:205], v[0:1] op_sel_hi:[1,0]
	v_cndmask_b32_e64 v211, v143, v47, s[42:43]
	v_cndmask_b32_e64 v210, v142, v46, s[42:43]
	v_min_f32_e32 v0, 0x41e6d4ca, v212
	v_pk_mul_f32 v[204:205], v[210:211], v[204:205]
	v_pk_mul_f32 v[210:211], v[44:45], s[8:9] op_sel_hi:[1,0]
	v_exp_f32_e32 v217, v0
	v_min_f32_e32 v0, 0x41e6d4ca, v213
	v_exp_f32_e32 v216, v0
	v_min_f32_e32 v0, 0x41e6d4ca, v210
	v_exp_f32_e32 v213, v0
	v_min_f32_e32 v0, 0x41e6d4ca, v211
	v_exp_f32_e32 v212, v0
	v_pk_add_f32 v[210:211], v[216:217], 1.0 op_sel_hi:[1,0]
	v_cvt_pk_bf16_f32 v204, v204, v205
	v_pk_add_f32 v[212:213], v[212:213], 1.0 op_sel_hi:[1,0]
	v_mul_f32_e32 v216, v211, v210
	v_mul_f32_e32 v217, v213, v212
	v_cndmask_b32_e64 v219, v141, v45, s[42:43]
	v_mul_f32_e32 v0, v216, v217
	v_rcp_f32_e32 v203, v0
	v_cndmask_b32_e64 v218, v140, v44, s[42:43]
	v_cvt_pk_bf16_f32 v205, v206, v207
	v_mul_f32_e32 v0, v217, v203
	v_mul_f32_e32 v216, v216, v203
	v_pk_mul_f32 v[210:211], v[210:211], v[0:1] op_sel_hi:[1,0]
	v_pk_mul_f32 v[212:213], v[212:213], v[216:217] op_sel_hi:[1,0]
	v_cndmask_b32_e64 v217, v139, v43, s[42:43]
	v_cndmask_b32_e64 v216, v138, v42, s[42:43]
	v_pk_mul_f32 v[212:213], v[218:219], v[212:213]
	v_pk_mul_f32 v[210:211], v[216:217], v[210:211]
	v_cvt_pk_bf16_f32 v207, v212, v213
	v_cvt_pk_bf16_f32 v206, v210, v211
	v_lshl_add_u64 v[210:211], v[174:175], 0, v[208:209]
	global_store_dwordx4 v[210:211], v[204:207], off
	v_lshl_add_u64 v[208:209], v[176:177], 0, v[208:209]
	s_nop 0
	v_pk_mul_f32 v[206:207], v[38:39], s[8:9] op_sel_hi:[1,0]
	v_pk_mul_f32 v[204:205], v[40:41], s[8:9] op_sel_hi:[1,0]
	v_min_f32_e32 v0, 0x41e6d4ca, v206
	v_exp_f32_e32 v211, v0
	v_min_f32_e32 v0, 0x41e6d4ca, v207
	v_exp_f32_e32 v210, v0
	v_min_f32_e32 v0, 0x41e6d4ca, v204
	v_exp_f32_e32 v207, v0
	v_min_f32_e32 v0, 0x41e6d4ca, v205
	v_exp_f32_e32 v206, v0
	v_pk_add_f32 v[204:205], v[210:211], 1.0 op_sel_hi:[1,0]
	v_pk_add_f32 v[206:207], v[206:207], 1.0 op_sel_hi:[1,0]
	v_mul_f32_e32 v210, v205, v204
	v_mul_f32_e32 v211, v207, v206
	v_cndmask_b32_e64 v213, v137, v41, s[42:43]
	v_mul_f32_e32 v0, v210, v211
	v_rcp_f32_e32 v203, v0
	v_cndmask_b32_e64 v212, v136, v40, s[42:43]
	v_mul_f32_e32 v210, v210, v203
	v_pk_mul_f32 v[206:207], v[206:207], v[210:211] op_sel_hi:[1,0]
	v_mul_f32_e32 v0, v211, v203
	v_pk_mul_f32 v[206:207], v[212:213], v[206:207]
	v_pk_mul_f32 v[212:213], v[34:35], s[8:9] op_sel_hi:[1,0]
	v_pk_mul_f32 v[204:205], v[204:205], v[0:1] op_sel_hi:[1,0]
	v_cndmask_b32_e64 v211, v135, v39, s[42:43]
	v_cndmask_b32_e64 v210, v134, v38, s[42:43]
	v_min_f32_e32 v0, 0x41e6d4ca, v212
	v_pk_mul_f32 v[204:205], v[210:211], v[204:205]
	v_pk_mul_f32 v[210:211], v[36:37], s[8:9] op_sel_hi:[1,0]
	v_exp_f32_e32 v217, v0
	v_min_f32_e32 v0, 0x41e6d4ca, v213
	v_exp_f32_e32 v216, v0
	v_min_f32_e32 v0, 0x41e6d4ca, v210
	v_exp_f32_e32 v213, v0
	v_min_f32_e32 v0, 0x41e6d4ca, v211
	v_exp_f32_e32 v212, v0
	v_pk_add_f32 v[210:211], v[216:217], 1.0 op_sel_hi:[1,0]
	v_cvt_pk_bf16_f32 v204, v204, v205
	v_pk_add_f32 v[212:213], v[212:213], 1.0 op_sel_hi:[1,0]
	v_mul_f32_e32 v216, v211, v210
	v_mul_f32_e32 v217, v213, v212
	v_cndmask_b32_e64 v219, v133, v37, s[42:43]
	v_mul_f32_e32 v0, v216, v217
	v_rcp_f32_e32 v203, v0
	v_cndmask_b32_e64 v218, v132, v36, s[42:43]
	v_cvt_pk_bf16_f32 v205, v206, v207
	v_mul_f32_e32 v0, v217, v203
	v_mul_f32_e32 v216, v216, v203
	v_pk_mul_f32 v[210:211], v[210:211], v[0:1] op_sel_hi:[1,0]
	v_pk_mul_f32 v[212:213], v[212:213], v[216:217] op_sel_hi:[1,0]
	v_cndmask_b32_e64 v217, v131, v35, s[42:43]
	v_cndmask_b32_e64 v216, v130, v34, s[42:43]
	v_pk_mul_f32 v[212:213], v[218:219], v[212:213]
	v_pk_mul_f32 v[210:211], v[216:217], v[210:211]
	v_cvt_pk_bf16_f32 v207, v212, v213
	v_cvt_pk_bf16_f32 v206, v210, v211
	v_add_u32_e32 v0, 0xa0, v202
	global_store_dwordx4 v[208:209], v[204:207], off
	v_ashrrev_i32_e32 v203, 31, v0
	v_mul_lo_u32 v203, s56, v203
	v_pk_mul_f32 v[206:207], v[30:31], s[8:9] op_sel_hi:[1,0]
	v_mul_lo_u32 v204, s57, v0
	v_mad_u64_u32 v[208:209], s[10:11], s56, v0, 0
	v_min_f32_e32 v0, 0x41e6d4ca, v206
	v_add3_u32 v209, v209, v203, v204
	v_pk_mul_f32 v[204:205], v[32:33], s[8:9] op_sel_hi:[1,0]
	v_exp_f32_e32 v211, v0
	v_min_f32_e32 v0, 0x41e6d4ca, v207
	v_exp_f32_e32 v210, v0
	v_min_f32_e32 v0, 0x41e6d4ca, v204
	v_exp_f32_e32 v207, v0
	v_min_f32_e32 v0, 0x41e6d4ca, v205
	v_exp_f32_e32 v206, v0
	v_pk_add_f32 v[204:205], v[210:211], 1.0 op_sel_hi:[1,0]
	v_lshlrev_b64 v[208:209], 1, v[208:209]
	v_pk_add_f32 v[206:207], v[206:207], 1.0 op_sel_hi:[1,0]
	v_mul_f32_e32 v210, v205, v204
	v_mul_f32_e32 v211, v207, v206
	v_cndmask_b32_e64 v213, v145, v33, s[42:43]
	v_mul_f32_e32 v0, v210, v211
	v_rcp_f32_e32 v203, v0
	v_cndmask_b32_e64 v212, v144, v32, s[42:43]
	v_lshl_add_u64 v[176:177], v[176:177], 0, v[208:209]
	v_cndmask_b32_e64 v145, v145, v17, s[42:43]
	v_mul_f32_e32 v210, v210, v203
	v_pk_mul_f32 v[206:207], v[206:207], v[210:211] op_sel_hi:[1,0]
	v_mul_f32_e32 v0, v211, v203
	v_pk_mul_f32 v[206:207], v[212:213], v[206:207]
	v_pk_mul_f32 v[212:213], v[26:27], s[8:9] op_sel_hi:[1,0]
	v_pk_mul_f32 v[204:205], v[204:205], v[0:1] op_sel_hi:[1,0]
	v_cndmask_b32_e64 v211, v143, v31, s[42:43]
	v_cndmask_b32_e64 v210, v142, v30, s[42:43]
	v_min_f32_e32 v0, 0x41e6d4ca, v212
	v_pk_mul_f32 v[204:205], v[210:211], v[204:205]
	v_pk_mul_f32 v[210:211], v[28:29], s[8:9] op_sel_hi:[1,0]
	v_exp_f32_e32 v217, v0
	v_min_f32_e32 v0, 0x41e6d4ca, v213
	v_exp_f32_e32 v216, v0
	v_min_f32_e32 v0, 0x41e6d4ca, v210
	v_exp_f32_e32 v213, v0
	v_min_f32_e32 v0, 0x41e6d4ca, v211
	v_exp_f32_e32 v212, v0
	v_pk_add_f32 v[210:211], v[216:217], 1.0 op_sel_hi:[1,0]
	v_cvt_pk_bf16_f32 v204, v204, v205
	v_pk_add_f32 v[212:213], v[212:213], 1.0 op_sel_hi:[1,0]
	v_mul_f32_e32 v216, v211, v210
	v_mul_f32_e32 v217, v213, v212
	v_cndmask_b32_e64 v219, v141, v29, s[42:43]
	v_mul_f32_e32 v0, v216, v217
	v_rcp_f32_e32 v203, v0
	v_cndmask_b32_e64 v218, v140, v28, s[42:43]
	v_cvt_pk_bf16_f32 v205, v206, v207
	v_cndmask_b32_e64 v144, v144, v16, s[42:43]
	v_mul_f32_e32 v0, v217, v203
	v_mul_f32_e32 v216, v216, v203
	v_pk_mul_f32 v[210:211], v[210:211], v[0:1] op_sel_hi:[1,0]
	v_pk_mul_f32 v[212:213], v[212:213], v[216:217] op_sel_hi:[1,0]
	v_cndmask_b32_e64 v217, v139, v27, s[42:43]
	v_cndmask_b32_e64 v216, v138, v26, s[42:43]
	v_pk_mul_f32 v[212:213], v[218:219], v[212:213]
	v_pk_mul_f32 v[210:211], v[216:217], v[210:211]
	v_cvt_pk_bf16_f32 v207, v212, v213
	v_cvt_pk_bf16_f32 v206, v210, v211
	v_lshl_add_u64 v[210:211], v[174:175], 0, v[208:209]
	global_store_dwordx4 v[210:211], v[204:207], off
	v_cndmask_b32_e64 v143, v143, v15, s[42:43]
	v_cndmask_b32_e64 v142, v142, v14, s[42:43]
	v_pk_mul_f32 v[206:207], v[22:23], s[8:9] op_sel_hi:[1,0]
	v_pk_mul_f32 v[204:205], v[24:25], s[8:9] op_sel_hi:[1,0]
	v_min_f32_e32 v0, 0x41e6d4ca, v206
	v_exp_f32_e32 v211, v0
	v_min_f32_e32 v0, 0x41e6d4ca, v207
	v_exp_f32_e32 v210, v0
	v_min_f32_e32 v0, 0x41e6d4ca, v204
	v_exp_f32_e32 v207, v0
	v_min_f32_e32 v0, 0x41e6d4ca, v205
	v_exp_f32_e32 v206, v0
	v_pk_add_f32 v[204:205], v[210:211], 1.0 op_sel_hi:[1,0]
	v_cndmask_b32_e64 v139, v139, v11, s[42:43]
	v_pk_add_f32 v[206:207], v[206:207], 1.0 op_sel_hi:[1,0]
	v_mul_f32_e32 v210, v205, v204
	v_mul_f32_e32 v211, v207, v206
	v_cndmask_b32_e64 v213, v137, v25, s[42:43]
	v_mul_f32_e32 v0, v210, v211
	v_rcp_f32_e32 v203, v0
	v_cndmask_b32_e64 v212, v136, v24, s[42:43]
	v_cndmask_b32_e64 v138, v138, v10, s[42:43]
	v_cndmask_b32_e64 v141, v141, v13, s[42:43]
	v_mul_f32_e32 v210, v210, v203
	v_pk_mul_f32 v[206:207], v[206:207], v[210:211] op_sel_hi:[1,0]
	v_mul_f32_e32 v0, v211, v203
	v_pk_mul_f32 v[206:207], v[212:213], v[206:207]
	v_pk_mul_f32 v[212:213], v[18:19], s[8:9] op_sel_hi:[1,0]
	v_pk_mul_f32 v[204:205], v[204:205], v[0:1] op_sel_hi:[1,0]
	v_cndmask_b32_e64 v211, v135, v23, s[42:43]
	v_cndmask_b32_e64 v210, v134, v22, s[42:43]
	v_min_f32_e32 v0, 0x41e6d4ca, v212
	v_pk_mul_f32 v[204:205], v[210:211], v[204:205]
	v_pk_mul_f32 v[210:211], v[20:21], s[8:9] op_sel_hi:[1,0]
	v_exp_f32_e32 v217, v0
	v_min_f32_e32 v0, 0x41e6d4ca, v213
	v_exp_f32_e32 v216, v0
	v_min_f32_e32 v0, 0x41e6d4ca, v210
	v_exp_f32_e32 v213, v0
	v_min_f32_e32 v0, 0x41e6d4ca, v211
	v_exp_f32_e32 v212, v0
	v_pk_add_f32 v[210:211], v[216:217], 1.0 op_sel_hi:[1,0]
	v_cvt_pk_bf16_f32 v204, v204, v205
	v_pk_add_f32 v[212:213], v[212:213], 1.0 op_sel_hi:[1,0]
	v_mul_f32_e32 v216, v211, v210
	v_mul_f32_e32 v217, v213, v212
	v_cndmask_b32_e64 v219, v133, v21, s[42:43]
	v_mul_f32_e32 v0, v216, v217
	v_rcp_f32_e32 v203, v0
	v_cndmask_b32_e64 v218, v132, v20, s[42:43]
	v_cvt_pk_bf16_f32 v205, v206, v207
	v_cndmask_b32_e64 v140, v140, v12, s[42:43]
	v_mul_f32_e32 v0, v217, v203
	v_mul_f32_e32 v216, v216, v203
	v_pk_mul_f32 v[210:211], v[210:211], v[0:1] op_sel_hi:[1,0]
	v_pk_mul_f32 v[212:213], v[212:213], v[216:217] op_sel_hi:[1,0]
	v_cndmask_b32_e64 v217, v131, v19, s[42:43]
	v_cndmask_b32_e64 v216, v130, v18, s[42:43]
	v_pk_mul_f32 v[212:213], v[218:219], v[212:213]
	v_pk_mul_f32 v[210:211], v[216:217], v[210:211]
	v_cvt_pk_bf16_f32 v207, v212, v213
	v_cvt_pk_bf16_f32 v206, v210, v211
	v_add_u32_e32 v0, 0xb0, v202
	global_store_dwordx4 v[176:177], v[204:207], off
	v_ashrrev_i32_e32 v176, 31, v0
	v_mul_lo_u32 v203, s56, v176
	v_pk_mul_f32 v[206:207], v[14:15], s[8:9] op_sel_hi:[1,0]
	v_mul_lo_u32 v204, s57, v0
	v_mad_u64_u32 v[176:177], s[10:11], s56, v0, 0
	v_min_f32_e32 v0, 0x41e6d4ca, v206
	v_add3_u32 v177, v177, v203, v204
	v_pk_mul_f32 v[204:205], v[16:17], s[8:9] op_sel_hi:[1,0]
	v_exp_f32_e32 v209, v0
	v_min_f32_e32 v0, 0x41e6d4ca, v207
	v_exp_f32_e32 v208, v0
	v_min_f32_e32 v0, 0x41e6d4ca, v204
	v_exp_f32_e32 v207, v0
	v_min_f32_e32 v0, 0x41e6d4ca, v205
	v_exp_f32_e32 v206, v0
	v_pk_add_f32 v[204:205], v[208:209], 1.0 op_sel_hi:[1,0]
	v_cndmask_b32_e64 v135, v135, v7, s[42:43]
	v_pk_add_f32 v[206:207], v[206:207], 1.0 op_sel_hi:[1,0]
	v_mul_f32_e32 v208, v205, v204
	v_mul_f32_e32 v209, v207, v206
	v_cndmask_b32_e64 v134, v134, v6, s[42:43]
	v_mul_f32_e32 v0, v208, v209
	v_rcp_f32_e32 v203, v0
	v_cndmask_b32_e64 v137, v137, v9, s[42:43]
	v_cndmask_b32_e64 v136, v136, v8, s[42:43]
	v_cndmask_b32_e64 v131, v131, v3, s[42:43]
	v_mul_f32_e32 v208, v208, v203
	v_pk_mul_f32 v[206:207], v[206:207], v[208:209] op_sel_hi:[1,0]
	v_mul_f32_e32 v0, v209, v203
	v_pk_mul_f32 v[144:145], v[144:145], v[206:207]
	v_pk_mul_f32 v[206:207], v[10:11], s[8:9] op_sel_hi:[1,0]
	v_pk_mul_f32 v[204:205], v[204:205], v[0:1] op_sel_hi:[1,0]
	v_min_f32_e32 v0, 0x41e6d4ca, v206
	v_pk_mul_f32 v[142:143], v[142:143], v[204:205]
	v_pk_mul_f32 v[204:205], v[12:13], s[8:9] op_sel_hi:[1,0]
	v_exp_f32_e32 v209, v0
	v_min_f32_e32 v0, 0x41e6d4ca, v207
	v_exp_f32_e32 v208, v0
	v_min_f32_e32 v0, 0x41e6d4ca, v204
	v_exp_f32_e32 v207, v0
	v_min_f32_e32 v0, 0x41e6d4ca, v205
	v_exp_f32_e32 v206, v0
	v_pk_add_f32 v[204:205], v[208:209], 1.0 op_sel_hi:[1,0]
	v_cndmask_b32_e64 v130, v130, v2, s[42:43]
	v_mov_b32_e32 v208, v205
	v_pk_add_f32 v[206:207], v[206:207], 1.0 op_sel_hi:[1,0]
	v_mov_b32_e32 v210, v204
	v_mov_b32_e32 v209, v207
	v_mov_b32_e32 v211, v206
	v_pk_mul_f32 v[208:209], v[208:209], v[210:211]
	v_cndmask_b32_e64 v133, v133, v5, s[42:43]
	v_mul_f32_e32 v0, v208, v209
	v_rcp_f32_e32 v203, v0
	v_cndmask_b32_e64 v132, v132, v4, s[42:43]
	s_mov_b64 s[10:11], 0
	v_mul_f32_e32 v0, v209, v203
	v_mul_f32_e32 v208, v208, v203
	v_pk_mul_f32 v[204:205], v[204:205], v[0:1] op_sel_hi:[1,0]
	v_pk_mul_f32 v[206:207], v[206:207], v[208:209] op_sel_hi:[1,0]
	s_nop 0
	v_pk_mul_f32 v[206:207], v[140:141], v[206:207]
	v_pk_mul_f32 v[140:141], v[138:139], v[204:205]
	v_cvt_pk_bf16_f32 v138, v142, v143
	v_cvt_pk_bf16_f32 v139, v144, v145
	v_cvt_pk_bf16_f32 v140, v140, v141
	v_cvt_pk_bf16_f32 v141, v206, v207
	v_lshl_add_u64 v[142:143], v[176:177], 1, v[174:175]
	global_store_dwordx4 v[142:143], v[138:141], off
	s_nop 1
	v_pk_mul_f32 v[140:141], v[6:7], s[8:9] op_sel_hi:[1,0]
	v_pk_mul_f32 v[138:139], v[8:9], s[8:9] op_sel_hi:[1,0]
	v_min_f32_e32 v0, 0x41e6d4ca, v140
	v_exp_f32_e32 v143, v0
	v_min_f32_e32 v0, 0x41e6d4ca, v141
	v_exp_f32_e32 v142, v0
	v_min_f32_e32 v0, 0x41e6d4ca, v138
	v_exp_f32_e32 v141, v0
	v_min_f32_e32 v0, 0x41e6d4ca, v139
	v_exp_f32_e32 v140, v0
	v_pk_add_f32 v[138:139], v[142:143], 1.0 op_sel_hi:[1,0]
	v_pk_add_f32 v[140:141], v[140:141], 1.0 op_sel_hi:[1,0]
	v_mul_f32_e32 v142, v139, v138
	v_mul_f32_e32 v143, v141, v140
	s_nop 0
	v_mul_f32_e32 v0, v142, v143
	v_rcp_f32_e32 v144, v0
	s_nop 0
	v_mul_f32_e32 v0, v143, v144
	v_pk_mul_f32 v[138:139], v[138:139], v[0:1] op_sel_hi:[1,0]
	v_mul_f32_e32 v142, v142, v144
	v_pk_mul_f32 v[134:135], v[134:135], v[138:139]
	v_pk_mul_f32 v[138:139], v[2:3], s[8:9] op_sel_hi:[1,0]
	v_pk_mul_f32 v[140:141], v[140:141], v[142:143] op_sel_hi:[1,0]
	v_min_f32_e32 v0, 0x41e6d4ca, v138
	v_pk_mul_f32 v[140:141], v[136:137], v[140:141]
	v_pk_mul_f32 v[136:137], v[4:5], s[8:9] op_sel_hi:[1,0]
	v_exp_f32_e32 v143, v0
	v_min_f32_e32 v0, 0x41e6d4ca, v139
	v_exp_f32_e32 v142, v0
	v_min_f32_e32 v0, 0x41e6d4ca, v136
	v_exp_f32_e32 v139, v0
	v_min_f32_e32 v0, 0x41e6d4ca, v137
	v_exp_f32_e32 v138, v0
	v_pk_add_f32 v[136:137], v[142:143], 1.0 op_sel_hi:[1,0]
	v_pk_add_f32 v[138:139], v[138:139], 1.0 op_sel_hi:[1,0]
	v_mul_f32_e32 v142, v137, v136
	v_mul_f32_e32 v143, v139, v138
	s_nop 0
	v_mul_f32_e32 v0, v142, v143
	v_rcp_f32_e32 v144, v0
	s_nop 0
	v_mul_f32_e32 v0, v143, v144
	v_mul_f32_e32 v142, v142, v144
	v_pk_mul_f32 v[144:145], v[136:137], v[0:1] op_sel_hi:[1,0]
	v_pk_mul_f32 v[136:137], v[138:139], v[142:143] op_sel_hi:[1,0]
	s_nop 0
	v_pk_mul_f32 v[136:137], v[132:133], v[136:137]
	v_pk_mul_f32 v[132:133], v[130:131], v[144:145]
	v_cvt_pk_bf16_f32 v130, v134, v135
	v_cvt_pk_bf16_f32 v131, v140, v141
	v_cvt_pk_bf16_f32 v132, v132, v133

.LBB0_768:
	v_pk_mul_f32 v[210:211], v[148:149], v[208:209] op_sel_hi:[1,0]
	v_mov_b32_e32 v148, 0
	v_mov_b32_e32 v149, 0
	s_waitcnt lgkmcnt(0)
	v_mov_b32_dpp v172, v164 row_shr:1 row_mask:0xf bank_mask:0xf
	v_mov_b32_dpp v173, v165 row_shr:1 row_mask:0xf bank_mask:0xf
	v_mov_b32_dpp v148, v210 row_ror:15 row_mask:0xf bank_mask:0xf
	v_mov_b32_dpp v149, v211 row_ror:15 row_mask:0xf bank_mask:0xf
	s_waitcnt vmcnt(0)
	v_pk_fma_f32 v[172:173], v[80:81], v[172:173], v[84:85]
	v_pk_mul_f32 v[206:207], v[150:151], v[208:209] op_sel_hi:[1,0]
	v_mov_b32_e32 v150, 0
	v_mov_b32_e32 v151, 0
	v_mov_b32_dpp v174, v166 row_shr:1 row_mask:0xf bank_mask:0xf
	v_mov_b32_dpp v175, v167 row_shr:1 row_mask:0xf bank_mask:0xf
	v_mov_b32_dpp v148, v164 row_shl:1 row_mask:0xf bank_mask:0xf
	v_mov_b32_dpp v149, v165 row_shl:1 row_mask:0xf bank_mask:0xf
	v_pk_fma_f32 v[172:173], v[164:165], v[76:77], v[172:173]
	v_mov_b32_dpp v150, v206 row_ror:15 row_mask:0xf bank_mask:0xf
	v_mov_b32_dpp v151, v207 row_ror:15 row_mask:0xf bank_mask:0xf
	v_pk_fma_f32 v[174:175], v[82:83], v[174:175], v[86:87]
	v_pk_fma_f32 v[148:149], v[72:73], v[148:149], v[172:173]
	v_mov_b32_dpp v150, v166 row_shl:1 row_mask:0xf bank_mask:0xf
	v_mov_b32_dpp v151, v167 row_shl:1 row_mask:0xf bank_mask:0xf
	v_pk_fma_f32 v[174:175], v[166:167], v[78:79], v[174:175]
	v_pk_mul_f32 v[172:173], v[148:149], v[148:149]
	v_pk_fma_f32 v[150:151], v[74:75], v[150:151], v[174:175]
	v_pk_mul_f32 v[172:173], v[148:149], v[172:173]
	v_pk_mul_f32 v[174:175], v[150:151], v[150:151]
	v_pk_fma_f32 v[172:173], v[172:173], s[70:71], v[148:149] op_sel_hi:[1,0,1]
	v_pk_mul_f32 v[174:175], v[150:151], v[174:175]
	v_pk_mul_f32 v[172:173], v[172:173], s[72:73] op_sel_hi:[1,0]
	v_pk_fma_f32 v[174:175], v[174:175], s[70:71], v[150:151] op_sel_hi:[1,0,1]
	v_min_f32_e32 v172, 0x41e6d4ca, v172
	v_pk_mul_f32 v[174:175], v[174:175], s[72:73] op_sel_hi:[1,0]
	v_exp_f32_e32 v233, v172
	v_min_f32_e32 v172, 0x41e6d4ca, v173
	v_exp_f32_e32 v232, v172
	v_min_f32_e32 v172, 0x41e6d4ca, v174
	v_exp_f32_e32 v173, v172
	v_min_f32_e32 v172, 0x41e6d4ca, v175
	v_exp_f32_e32 v172, v172
	v_mov_b32_e32 v230, v212
	v_mov_b32_e32 v231, v212
	v_pk_mul_f32 v[146:147], v[146:147], v[230:231]
	v_pk_mul_f32 v[144:145], v[144:145], v[212:213]
	v_pk_mul_f32 v[138:139], v[138:139], v[230:231]
	v_pk_mul_f32 v[136:137], v[136:137], v[212:213]
	v_pk_add_f32 v[212:213], v[232:233], 1.0 op_sel_hi:[1,0]
	v_pk_add_f32 v[230:231], v[172:173], 1.0 op_sel_hi:[1,0]
	v_mul_f32_e32 v232, v213, v212
	v_mul_f32_e32 v233, v231, v230
	v_pk_mul_f32 v[174:175], v[140:141], v[208:209] op_sel_hi:[1,0]
	v_mul_f32_e32 v172, v232, v233
	v_rcp_f32_e32 v199, v172
	v_mov_b32_dpp v168, v160 row_shr:1 row_mask:0xf bank_mask:0xf
	v_mov_b32_dpp v169, v161 row_shr:1 row_mask:0xf bank_mask:0xf
	v_pk_fma_f32 v[168:169], v[64:65], v[168:169], v[68:69]
	v_mul_f32_e32 v140, v232, v199
	v_pk_mul_f32 v[230:231], v[230:231], v[140:141] op_sel_hi:[1,0]
	v_mov_b32_e32 v140, 0
	v_mov_b32_e32 v141, 0
	v_pk_mul_f32 v[172:173], v[142:143], v[208:209] op_sel_hi:[1,0]
	v_mov_b32_dpp v140, v174 row_ror:15 row_mask:0xf bank_mask:0xf
	v_mov_b32_dpp v141, v175 row_ror:15 row_mask:0xf bank_mask:0xf
	v_mov_b32_e32 v142, 0
	v_mov_b32_e32 v143, 0
	v_mov_b32_dpp v170, v162 row_shr:1 row_mask:0xf bank_mask:0xf
	v_mov_b32_dpp v171, v163 row_shr:1 row_mask:0xf bank_mask:0xf
	v_mov_b32_dpp v140, v160 row_shl:1 row_mask:0xf bank_mask:0xf
	v_mov_b32_dpp v141, v161 row_shl:1 row_mask:0xf bank_mask:0xf
	v_pk_fma_f32 v[168:169], v[160:161], v[60:61], v[168:169]
	v_mov_b32_dpp v142, v172 row_ror:15 row_mask:0xf bank_mask:0xf
	v_mov_b32_dpp v143, v173 row_ror:15 row_mask:0xf bank_mask:0xf
	v_pk_fma_f32 v[170:171], v[66:67], v[170:171], v[70:71]
	v_pk_fma_f32 v[140:141], v[56:57], v[140:141], v[168:169]
	v_mov_b32_dpp v142, v162 row_shl:1 row_mask:0xf bank_mask:0xf
	v_mov_b32_dpp v143, v163 row_shl:1 row_mask:0xf bank_mask:0xf
	v_pk_fma_f32 v[170:171], v[162:163], v[62:63], v[170:171]
	v_pk_mul_f32 v[168:169], v[140:141], v[140:141]
	v_pk_fma_f32 v[142:143], v[58:59], v[142:143], v[170:171]
	v_pk_mul_f32 v[168:169], v[140:141], v[168:169]
	v_pk_mul_f32 v[170:171], v[142:143], v[142:143]
	v_pk_fma_f32 v[168:169], v[168:169], s[70:71], v[140:141] op_sel_hi:[1,0,1]
	v_pk_mul_f32 v[170:171], v[142:143], v[170:171]
	v_pk_mul_f32 v[168:169], v[168:169], s[72:73] op_sel_hi:[1,0]
	v_pk_fma_f32 v[170:171], v[170:171], s[70:71], v[142:143] op_sel_hi:[1,0,1]
	v_min_f32_e32 v168, 0x41e6d4ca, v168
	v_mul_f32_e32 v234, v233, v199
	v_pk_mul_f32 v[170:171], v[170:171], s[72:73] op_sel_hi:[1,0]
	v_exp_f32_e32 v233, v168
	v_min_f32_e32 v168, 0x41e6d4ca, v169
	v_exp_f32_e32 v232, v168
	v_min_f32_e32 v168, 0x41e6d4ca, v170
	v_exp_f32_e32 v169, v168
	v_min_f32_e32 v168, 0x41e6d4ca, v171
	v_exp_f32_e32 v168, v168
	v_pk_mul_f32 v[170:171], v[212:213], v[234:235] op_sel_hi:[1,0]
	v_pk_add_f32 v[212:213], v[232:233], 1.0 op_sel_hi:[1,0]
	v_pk_mul_f32 v[170:171], v[148:149], v[170:171]
	v_pk_add_f32 v[168:169], v[168:169], 1.0 op_sel_hi:[1,0]
	v_mov_b32_e32 v232, v213
	v_mov_b32_e32 v233, v169
	v_mov_b32_e32 v234, v212
	v_mov_b32_e32 v235, v168
	v_pk_mul_f32 v[232:233], v[232:233], v[234:235]
	v_pk_mul_f32 v[170:171], v[144:145], v[170:171]
	v_mul_f32_e32 v199, v232, v233
	v_rcp_f32_e32 v199, v199
	v_add_u32_e32 v197, s11, v217
	v_pk_mul_f32 v[230:231], v[150:151], v[230:231]
	s_lshl_b32 s12, s10, 1
	v_mul_f32_e32 v234, v233, v199
	v_mul_f32_e32 v232, v232, v199
	v_pk_mul_f32 v[212:213], v[212:213], v[234:235] op_sel_hi:[1,0]
	v_pk_mul_f32 v[168:169], v[168:169], v[232:233] op_sel_hi:[1,0]
	v_pk_mul_f32 v[212:213], v[140:141], v[212:213]
	v_pk_mul_f32 v[168:169], v[142:143], v[168:169]
	v_pk_mul_f32 v[212:213], v[136:137], v[212:213]
	v_pk_mul_f32 v[232:233], v[138:139], v[168:169]
	v_cvt_pk_bf16_f32 v168, v170, v171
	v_cvt_pk_bf16_f32 v170, v212, v213
	v_mov_b64_e32 v[212:213], s[86:87]
	s_mul_i32 s15, s10, 0x10800
	v_pk_mul_f32 v[230:231], v[146:147], v[230:231]
	v_mad_i64_i32 v[212:213], s[10:11], v197, s90, v[212:213]
	s_mul_hi_i32 s16, s12, 0x8400
	v_cvt_pk_bf16_f32 v169, v230, v231
	v_cvt_pk_bf16_f32 v171, v232, v233
	v_lshl_add_u64 v[212:213], v[192:193], 1, v[212:213]
	global_store_dwordx4 v[212:213], v[168:171], off
	s_and_saveexec_b64 s[10:11], s[40:41]
	s_cbranch_execz .LBB0_770
	s_add_u32 s24, s4, s15
	s_addc_u32 s25, s5, s16
	v_lshl_add_u64 v[168:169], v[192:193], 2, s[24:25]
	global_store_dwordx4 v[168:169], v[148:151], off
	s_nop 1
	v_add_co_u32_e32 v148, vcc, 0x2000, v168
	s_nop 1
	v_addc_co_u32_e32 v149, vcc, 0, v169, vcc
	v_add_co_u32_e32 v150, vcc, 0x5000, v168
	global_store_dwordx4 v[148:149], v[164:167], off offset:3072
	s_nop 0
	v_addc_co_u32_e32 v151, vcc, 0, v169, vcc
	global_store_dwordx4 v[150:151], v[144:147], off offset:2048
	global_store_dwordx4 v[168:169], v[140:143], off offset:16
	global_store_dwordx4 v[148:149], v[160:163], off offset:3088
	global_store_dwordx4 v[150:151], v[136:139], off offset:2064
.LBB0_770:
	s_or_b64 exec, exec, s[10:11]
	v_mov_b32_e32 v209, v208
	v_pk_mul_f32 v[140:141], v[116:117], v[208:209]
	v_pk_mul_f32 v[116:117], v[120:121], v[202:203] op_sel_hi:[1,0]
	v_mov_b32_e32 v120, v204
	v_mov_b32_e32 v121, v204
	v_pk_mul_f32 v[102:103], v[102:103], v[120:121]
	v_pk_mul_f32 v[98:99], v[98:99], v[120:121]
	v_mov_b32_e32 v120, 0
	v_mov_b32_e32 v121, 0
	v_mov_b32_e32 v136, v208
	v_mov_b32_e32 v137, v208
	v_mov_b32_dpp v120, v164 row_ror:1 row_mask:0xf bank_mask:0xf
	v_mov_b32_dpp v121, v165 row_ror:1 row_mask:0xf bank_mask:0xf
	v_pk_mul_f32 v[138:139], v[118:119], v[136:137]
	v_pk_mul_f32 v[136:137], v[114:115], v[136:137]
	v_pk_mul_f32 v[118:119], v[126:127], v[202:203] op_sel_hi:[1,0]
	v_pk_mul_f32 v[124:125], v[124:125], v[202:203] op_sel_hi:[1,0]
	v_pk_mul_f32 v[114:115], v[122:123], v[202:203] op_sel_hi:[1,0]
	v_mov_b32_e32 v122, 0
	v_mov_b32_e32 v123, 0
	v_mov_b32_e32 v126, 0
	v_mov_b32_e32 v127, 0
	v_mov_b32_dpp v120, v210 row_shr:1 row_mask:0xf bank_mask:0xf
	v_mov_b32_dpp v121, v211 row_shr:1 row_mask:0xf bank_mask:0xf
	v_mov_b32_dpp v122, v166 row_ror:1 row_mask:0xf bank_mask:0xf
	v_mov_b32_dpp v123, v167 row_ror:1 row_mask:0xf bank_mask:0xf
	v_mov_b32_dpp v126, v124 row_ror:15 row_mask:0xf bank_mask:0xf
	v_mov_b32_dpp v127, v125 row_ror:15 row_mask:0xf bank_mask:0xf
	v_pk_fma_f32 v[120:121], v[80:81], v[120:121], v[84:85]
	v_mov_b32_e32 v142, 0
	v_mov_b32_e32 v143, 0
	v_mov_b32_dpp v122, v206 row_shr:1 row_mask:0xf bank_mask:0xf
	v_mov_b32_dpp v123, v207 row_shr:1 row_mask:0xf bank_mask:0xf
	v_mov_b32_dpp v126, v210 row_shl:1 row_mask:0xf bank_mask:0xf
	v_mov_b32_dpp v127, v211 row_shl:1 row_mask:0xf bank_mask:0xf
	v_pk_fma_f32 v[120:121], v[210:211], v[76:77], v[120:121]
	v_mov_b32_dpp v142, v118 row_ror:15 row_mask:0xf bank_mask:0xf
	v_mov_b32_dpp v143, v119 row_ror:15 row_mask:0xf bank_mask:0xf
	v_pk_fma_f32 v[122:123], v[82:83], v[122:123], v[86:87]
	v_pk_fma_f32 v[120:121], v[72:73], v[126:127], v[120:121]
	v_mov_b32_dpp v142, v206 row_shl:1 row_mask:0xf bank_mask:0xf
	v_mov_b32_dpp v143, v207 row_shl:1 row_mask:0xf bank_mask:0xf
	v_pk_fma_f32 v[122:123], v[206:207], v[78:79], v[122:123]
	v_pk_mul_f32 v[126:127], v[120:121], v[120:121]
	v_pk_fma_f32 v[122:123], v[74:75], v[142:143], v[122:123]
	v_pk_mul_f32 v[126:127], v[120:121], v[126:127]
	v_pk_mul_f32 v[142:143], v[122:123], v[122:123]
	v_pk_fma_f32 v[126:127], v[126:127], s[70:71], v[120:121] op_sel_hi:[1,0,1]
	v_pk_mul_f32 v[142:143], v[122:123], v[142:143]
	v_pk_mul_f32 v[126:127], v[126:127], s[72:73] op_sel_hi:[1,0]
	v_pk_fma_f32 v[142:143], v[142:143], s[70:71], v[122:123] op_sel_hi:[1,0,1]
	v_min_f32_e32 v126, 0x41e6d4ca, v126
	v_pk_mul_f32 v[142:143], v[142:143], s[72:73] op_sel_hi:[1,0]
	v_exp_f32_e32 v145, v126
	v_min_f32_e32 v126, 0x41e6d4ca, v127
	v_exp_f32_e32 v144, v126
	v_min_f32_e32 v126, 0x41e6d4ca, v142
	v_exp_f32_e32 v127, v126
	v_min_f32_e32 v126, 0x41e6d4ca, v143
	v_exp_f32_e32 v126, v126
	v_pk_add_f32 v[142:143], v[144:145], 1.0 op_sel_hi:[1,0]
	v_pk_mul_f32 v[112:113], v[112:113], v[208:209]
	v_pk_add_f32 v[126:127], v[126:127], 1.0 op_sel_hi:[1,0]
	v_mul_f32_e32 v144, v143, v142
	v_mul_f32_e32 v145, v127, v126
	v_or_b32_e32 v148, 16, v197
	v_mul_f32_e32 v146, v144, v145
	v_rcp_f32_e32 v147, v146
	v_pk_mul_f32 v[108:109], v[108:109], v[202:203] op_sel_hi:[1,0]
	v_pk_mul_f32 v[110:111], v[110:111], v[202:203] op_sel_hi:[1,0]
	v_pk_mul_f32 v[106:107], v[106:107], v[202:203] op_sel_hi:[1,0]
	v_mul_f32_e32 v144, v144, v147
	v_mul_f32_e32 v146, v145, v147
	v_pk_mul_f32 v[126:127], v[126:127], v[144:145] op_sel_hi:[1,0]
	v_pk_mul_f32 v[142:143], v[142:143], v[146:147] op_sel_hi:[1,0]
	v_pk_mul_f32 v[122:123], v[122:123], v[126:127]
	v_mov_b32_e32 v126, 0
	v_mov_b32_e32 v127, 0
	v_pk_mul_f32 v[120:121], v[120:121], v[142:143]
	v_mov_b32_dpp v126, v160 row_ror:1 row_mask:0xf bank_mask:0xf
	v_mov_b32_dpp v127, v161 row_ror:1 row_mask:0xf bank_mask:0xf
	v_pk_mul_f32 v[122:123], v[138:139], v[122:123]
	v_pk_mul_f32 v[120:121], v[140:141], v[120:121]
	v_mov_b32_e32 v138, 0
	v_mov_b32_e32 v139, 0
	v_mov_b32_e32 v140, 0
	v_mov_b32_e32 v141, 0
	v_mov_b32_dpp v126, v174 row_shr:1 row_mask:0xf bank_mask:0xf
	v_mov_b32_dpp v127, v175 row_shr:1 row_mask:0xf bank_mask:0xf
	v_mov_b32_dpp v138, v162 row_ror:1 row_mask:0xf bank_mask:0xf
	v_mov_b32_dpp v139, v163 row_ror:1 row_mask:0xf bank_mask:0xf
	v_mov_b32_dpp v140, v116 row_ror:15 row_mask:0xf bank_mask:0xf
	v_mov_b32_dpp v141, v117 row_ror:15 row_mask:0xf bank_mask:0xf
	v_pk_fma_f32 v[126:127], v[64:65], v[126:127], v[68:69]
	v_mov_b32_e32 v142, 0
	v_mov_b32_e32 v143, 0
	v_mov_b32_dpp v138, v172 row_shr:1 row_mask:0xf bank_mask:0xf
	v_mov_b32_dpp v139, v173 row_shr:1 row_mask:0xf bank_mask:0xf
	v_mov_b32_dpp v140, v174 row_shl:1 row_mask:0xf bank_mask:0xf
	v_mov_b32_dpp v141, v175 row_shl:1 row_mask:0xf bank_mask:0xf
	v_pk_fma_f32 v[126:127], v[174:175], v[60:61], v[126:127]
	v_mov_b32_dpp v142, v114 row_ror:15 row_mask:0xf bank_mask:0xf
	v_mov_b32_dpp v143, v115 row_ror:15 row_mask:0xf bank_mask:0xf
	v_pk_fma_f32 v[138:139], v[66:67], v[138:139], v[70:71]
	v_pk_fma_f32 v[126:127], v[56:57], v[140:141], v[126:127]
	v_mov_b32_dpp v142, v172 row_shl:1 row_mask:0xf bank_mask:0xf
	v_mov_b32_dpp v143, v173 row_shl:1 row_mask:0xf bank_mask:0xf
	v_pk_fma_f32 v[138:139], v[172:173], v[62:63], v[138:139]
	v_pk_mul_f32 v[140:141], v[126:127], v[126:127]
	v_pk_fma_f32 v[138:139], v[58:59], v[142:143], v[138:139]
	v_pk_mul_f32 v[140:141], v[126:127], v[140:141]
	v_pk_mul_f32 v[142:143], v[138:139], v[138:139]
	v_pk_fma_f32 v[140:141], v[140:141], s[70:71], v[126:127] op_sel_hi:[1,0,1]
	v_pk_mul_f32 v[142:143], v[138:139], v[142:143]
	v_pk_mul_f32 v[140:141], v[140:141], s[72:73] op_sel_hi:[1,0]
	v_pk_fma_f32 v[142:143], v[142:143], s[70:71], v[138:139] op_sel_hi:[1,0,1]
	v_min_f32_e32 v140, 0x41e6d4ca, v140
	v_pk_mul_f32 v[142:143], v[142:143], s[72:73] op_sel_hi:[1,0]
	v_exp_f32_e32 v145, v140
	v_min_f32_e32 v140, 0x41e6d4ca, v141
	v_exp_f32_e32 v144, v140
	v_min_f32_e32 v140, 0x41e6d4ca, v142
	v_exp_f32_e32 v141, v140
	v_min_f32_e32 v140, 0x41e6d4ca, v143
	v_exp_f32_e32 v140, v140
	v_pk_add_f32 v[142:143], v[144:145], 1.0 op_sel_hi:[1,0]
	v_pk_mul_f32 v[104:105], v[104:105], v[202:203] op_sel_hi:[1,0]
	v_pk_add_f32 v[140:141], v[140:141], 1.0 op_sel_hi:[1,0]
	v_mul_f32_e32 v144, v143, v142
	v_mul_f32_e32 v145, v141, v140
	v_mov_b32_dpp v156, v132 row_shl:1 row_mask:0xf bank_mask:0xf
	v_mul_f32_e32 v146, v144, v145
	v_rcp_f32_e32 v147, v146
	v_mov_b32_dpp v157, v133 row_shl:1 row_mask:0xf bank_mask:0xf
	v_mov_b32_dpp v158, v134 row_shl:1 row_mask:0xf bank_mask:0xf
	v_mov_b32_dpp v159, v135 row_shl:1 row_mask:0xf bank_mask:0xf
	v_mul_f32_e32 v146, v145, v147
	v_mul_f32_e32 v144, v144, v147
	v_pk_mul_f32 v[140:141], v[140:141], v[144:145] op_sel_hi:[1,0]
	v_pk_mul_f32 v[142:143], v[142:143], v[146:147] op_sel_hi:[1,0]
	v_pk_mul_f32 v[138:139], v[138:139], v[140:141]
	v_pk_mul_f32 v[126:127], v[126:127], v[142:143]
	v_pk_mul_f32 v[140:141], v[136:137], v[138:139]
	v_pk_mul_f32 v[112:113], v[112:113], v[126:127]
	v_cvt_pk_bf16_f32 v136, v120, v121
	v_mov_b64_e32 v[120:121], s[86:87]
	v_cvt_pk_bf16_f32 v137, v122, v123
	v_cvt_pk_bf16_f32 v138, v112, v113
	v_mad_i64_i32 v[122:123], s[10:11], v148, s90, v[120:121]
	v_lshlrev_b64 v[112:113], 1, v[192:193]
	v_cvt_pk_bf16_f32 v139, v140, v141
	v_lshl_add_u64 v[122:123], v[122:123], 0, v[112:113]
	global_store_dwordx4 v[122:123], v[136:139], off
	v_mov_b32_e32 v122, 0
	v_mov_b32_e32 v123, 0
	v_mov_b32_e32 v126, 0
	v_mov_b32_dpp v122, v210 row_ror:1 row_mask:0xf bank_mask:0xf
	v_mov_b32_dpp v123, v211 row_ror:1 row_mask:0xf bank_mask:0xf
	v_mov_b32_e32 v127, 0
	v_mov_b32_e32 v136, 0
	v_mov_b32_e32 v137, 0
	v_mov_b32_dpp v122, v124 row_shr:1 row_mask:0xf bank_mask:0xf
	v_mov_b32_dpp v123, v125 row_shr:1 row_mask:0xf bank_mask:0xf
	v_mov_b32_dpp v126, v206 row_ror:1 row_mask:0xf bank_mask:0xf
	v_mov_b32_dpp v127, v207 row_ror:1 row_mask:0xf bank_mask:0xf
	v_mov_b32_dpp v136, v132 row_ror:15 row_mask:0xf bank_mask:0xf
	v_mov_b32_dpp v137, v133 row_ror:15 row_mask:0xf bank_mask:0xf
	v_pk_fma_f32 v[122:123], v[80:81], v[122:123], v[84:85]
	v_mov_b32_e32 v138, 0
	v_mov_b32_e32 v139, 0
	v_mov_b32_dpp v126, v118 row_shr:1 row_mask:0xf bank_mask:0xf
	v_mov_b32_dpp v127, v119 row_shr:1 row_mask:0xf bank_mask:0xf
	v_mov_b32_dpp v136, v124 row_shl:1 row_mask:0xf bank_mask:0xf
	v_mov_b32_dpp v137, v125 row_shl:1 row_mask:0xf bank_mask:0xf
	v_pk_fma_f32 v[122:123], v[124:125], v[76:77], v[122:123]
	v_mov_b32_dpp v138, v134 row_ror:15 row_mask:0xf bank_mask:0xf
	v_mov_b32_dpp v139, v135 row_ror:15 row_mask:0xf bank_mask:0xf
	v_pk_fma_f32 v[126:127], v[82:83], v[126:127], v[86:87]
	v_pk_fma_f32 v[122:123], v[72:73], v[136:137], v[122:123]
	v_mov_b32_dpp v138, v118 row_shl:1 row_mask:0xf bank_mask:0xf
	v_mov_b32_dpp v139, v119 row_shl:1 row_mask:0xf bank_mask:0xf
	v_pk_fma_f32 v[126:127], v[118:119], v[78:79], v[126:127]
	v_pk_mul_f32 v[136:137], v[122:123], v[122:123]
	v_pk_fma_f32 v[126:127], v[74:75], v[138:139], v[126:127]
	v_pk_mul_f32 v[136:137], v[122:123], v[136:137]
	v_pk_mul_f32 v[138:139], v[126:127], v[126:127]
	v_pk_fma_f32 v[136:137], v[136:137], s[70:71], v[122:123] op_sel_hi:[1,0,1]
	v_pk_mul_f32 v[138:139], v[126:127], v[138:139]
	v_pk_mul_f32 v[136:137], v[136:137], s[72:73] op_sel_hi:[1,0]
	v_pk_fma_f32 v[138:139], v[138:139], s[70:71], v[126:127] op_sel_hi:[1,0,1]
	v_min_f32_e32 v136, 0x41e6d4ca, v136
	v_pk_mul_f32 v[138:139], v[138:139], s[72:73] op_sel_hi:[1,0]
	v_exp_f32_e32 v141, v136
	v_min_f32_e32 v136, 0x41e6d4ca, v137
	v_exp_f32_e32 v140, v136
	v_min_f32_e32 v136, 0x41e6d4ca, v138
	v_exp_f32_e32 v137, v136
	v_min_f32_e32 v136, 0x41e6d4ca, v139
	v_exp_f32_e32 v136, v136
	v_pk_add_f32 v[138:139], v[140:141], 1.0 op_sel_hi:[1,0]
	v_or_b32_e32 v144, 32, v197
	v_pk_add_f32 v[136:137], v[136:137], 1.0 op_sel_hi:[1,0]
	v_mul_f32_e32 v140, v139, v138
	v_mul_f32_e32 v141, v137, v136
	v_pk_mul_f32 v[100:101], v[100:101], v[204:205]
	v_mul_f32_e32 v142, v140, v141
	v_rcp_f32_e32 v143, v142
	v_mov_b32_dpp v152, v128 row_shl:1 row_mask:0xf bank_mask:0xf
	v_mov_b32_dpp v153, v129 row_shl:1 row_mask:0xf bank_mask:0xf
	v_mov_b32_dpp v154, v130 row_shl:1 row_mask:0xf bank_mask:0xf
	v_mul_f32_e32 v142, v141, v143
	v_pk_mul_f32 v[138:139], v[138:139], v[142:143] op_sel_hi:[1,0]
	v_mul_f32_e32 v140, v140, v143
	v_pk_mul_f32 v[122:123], v[122:123], v[138:139]
	v_pk_mul_f32 v[136:137], v[136:137], v[140:141] op_sel_hi:[1,0]
	v_pk_mul_f32 v[108:109], v[108:109], v[122:123]
	v_mov_b32_e32 v122, 0
	v_mov_b32_e32 v123, 0
	v_pk_mul_f32 v[126:127], v[126:127], v[136:137]
	v_mov_b32_dpp v122, v174 row_ror:1 row_mask:0xf bank_mask:0xf
	v_mov_b32_dpp v123, v175 row_ror:1 row_mask:0xf bank_mask:0xf
	v_pk_mul_f32 v[110:111], v[110:111], v[126:127]
	v_mov_b32_e32 v126, 0
	v_mov_b32_e32 v127, 0
	v_mov_b32_e32 v136, 0
	v_mov_b32_e32 v137, 0
	v_mov_b32_dpp v122, v116 row_shr:1 row_mask:0xf bank_mask:0xf
	v_mov_b32_dpp v123, v117 row_shr:1 row_mask:0xf bank_mask:0xf
	v_mov_b32_dpp v126, v172 row_ror:1 row_mask:0xf bank_mask:0xf
	v_mov_b32_dpp v127, v173 row_ror:1 row_mask:0xf bank_mask:0xf
	v_mov_b32_dpp v136, v128 row_ror:15 row_mask:0xf bank_mask:0xf
	v_mov_b32_dpp v137, v129 row_ror:15 row_mask:0xf bank_mask:0xf
	v_pk_fma_f32 v[122:123], v[64:65], v[122:123], v[68:69]
	v_mov_b32_e32 v138, 0
	v_mov_b32_e32 v139, 0
	v_mov_b32_dpp v126, v114 row_shr:1 row_mask:0xf bank_mask:0xf
	v_mov_b32_dpp v127, v115 row_shr:1 row_mask:0xf bank_mask:0xf
	v_mov_b32_dpp v136, v116 row_shl:1 row_mask:0xf bank_mask:0xf
	v_mov_b32_dpp v137, v117 row_shl:1 row_mask:0xf bank_mask:0xf
	v_pk_fma_f32 v[122:123], v[116:117], v[60:61], v[122:123]
	v_mov_b32_dpp v138, v130 row_ror:15 row_mask:0xf bank_mask:0xf
	v_mov_b32_dpp v139, v131 row_ror:15 row_mask:0xf bank_mask:0xf
	v_pk_fma_f32 v[126:127], v[66:67], v[126:127], v[70:71]
	v_pk_fma_f32 v[122:123], v[56:57], v[136:137], v[122:123]
	v_mov_b32_dpp v138, v114 row_shl:1 row_mask:0xf bank_mask:0xf
	v_mov_b32_dpp v139, v115 row_shl:1 row_mask:0xf bank_mask:0xf
	v_pk_fma_f32 v[126:127], v[114:115], v[62:63], v[126:127]
	v_pk_mul_f32 v[136:137], v[122:123], v[122:123]
	v_pk_fma_f32 v[126:127], v[58:59], v[138:139], v[126:127]
	v_pk_mul_f32 v[136:137], v[122:123], v[136:137]
	v_pk_mul_f32 v[138:139], v[126:127], v[126:127]
	v_pk_fma_f32 v[136:137], v[136:137], s[70:71], v[122:123] op_sel_hi:[1,0,1]
	v_pk_mul_f32 v[138:139], v[126:127], v[138:139]
	v_pk_mul_f32 v[136:137], v[136:137], s[72:73] op_sel_hi:[1,0]
	v_pk_fma_f32 v[138:139], v[138:139], s[70:71], v[126:127] op_sel_hi:[1,0,1]
	v_min_f32_e32 v136, 0x41e6d4ca, v136
	v_pk_mul_f32 v[138:139], v[138:139], s[72:73] op_sel_hi:[1,0]
	v_exp_f32_e32 v141, v136
	v_min_f32_e32 v136, 0x41e6d4ca, v137
	v_exp_f32_e32 v140, v136
	v_min_f32_e32 v136, 0x41e6d4ca, v138
	v_exp_f32_e32 v137, v136
	v_min_f32_e32 v136, 0x41e6d4ca, v139
	v_exp_f32_e32 v136, v136
	v_pk_add_f32 v[138:139], v[140:141], 1.0 op_sel_hi:[1,0]
	v_mov_b32_dpp v155, v131 row_shl:1 row_mask:0xf bank_mask:0xf
	v_pk_add_f32 v[136:137], v[136:137], 1.0 op_sel_hi:[1,0]
	v_mul_f32_e32 v140, v139, v138
	v_mul_f32_e32 v141, v137, v136
	v_pk_mul_f32 v[96:97], v[96:97], v[204:205]
	v_mul_f32_e32 v142, v140, v141
	v_rcp_f32_e32 v143, v142
	s_or_b32 s14, s12, 1
	s_mul_hi_i32 s12, s14, 0x8400
	s_mul_i32 s14, s14, 0x8400
	v_mul_f32_e32 v142, v141, v143
	v_mul_f32_e32 v140, v140, v143
	v_pk_mul_f32 v[136:137], v[136:137], v[140:141] op_sel_hi:[1,0]
	v_pk_mul_f32 v[138:139], v[138:139], v[142:143] op_sel_hi:[1,0]
	v_pk_mul_f32 v[126:127], v[126:127], v[136:137]
	v_pk_mul_f32 v[122:123], v[122:123], v[138:139]
	v_pk_mul_f32 v[126:127], v[106:107], v[126:127]
	v_pk_mul_f32 v[106:107], v[104:105], v[122:123]
	v_cvt_pk_bf16_f32 v104, v108, v109
	v_mad_i64_i32 v[108:109], s[10:11], v144, s90, v[120:121]
	v_cvt_pk_bf16_f32 v105, v110, v111
	v_cvt_pk_bf16_f32 v106, v106, v107
	v_cvt_pk_bf16_f32 v107, v126, v127
	v_lshl_add_u64 v[108:109], v[108:109], 0, v[112:113]
	global_store_dwordx4 v[108:109], v[104:107], off
	v_or_b32_e32 v136, 48, v197
	s_nop 0
	v_mov_b32_e32 v104, 0
	v_mov_b32_e32 v105, 0
	v_mov_b32_e32 v106, 0
	v_mov_b32_dpp v104, v124 row_ror:1 row_mask:0xf bank_mask:0xf
	v_mov_b32_dpp v105, v125 row_ror:1 row_mask:0xf bank_mask:0xf
	v_mov_b32_e32 v107, 0
	v_mov_b32_dpp v104, v132 row_shr:1 row_mask:0xf bank_mask:0xf
	v_mov_b32_dpp v105, v133 row_shr:1 row_mask:0xf bank_mask:0xf
	v_mov_b32_dpp v106, v118 row_ror:1 row_mask:0xf bank_mask:0xf
	v_mov_b32_dpp v107, v119 row_ror:1 row_mask:0xf bank_mask:0xf
	v_pk_fma_f32 v[104:105], v[80:81], v[104:105], v[84:85]
	v_mov_b32_dpp v106, v134 row_shr:1 row_mask:0xf bank_mask:0xf
	v_mov_b32_dpp v107, v135 row_shr:1 row_mask:0xf bank_mask:0xf
	v_pk_fma_f32 v[104:105], v[132:133], v[76:77], v[104:105]
	v_pk_fma_f32 v[106:107], v[82:83], v[106:107], v[86:87]
	v_pk_fma_f32 v[104:105], v[72:73], v[156:157], v[104:105]
	v_pk_fma_f32 v[106:107], v[134:135], v[78:79], v[106:107]
	v_pk_mul_f32 v[108:109], v[104:105], v[104:105]
	v_pk_fma_f32 v[106:107], v[74:75], v[158:159], v[106:107]
	v_pk_mul_f32 v[108:109], v[104:105], v[108:109]
	v_pk_mul_f32 v[110:111], v[106:107], v[106:107]
	v_pk_fma_f32 v[108:109], v[108:109], s[70:71], v[104:105] op_sel_hi:[1,0,1]
	v_pk_mul_f32 v[110:111], v[106:107], v[110:111]
	v_pk_mul_f32 v[108:109], v[108:109], s[72:73] op_sel_hi:[1,0]
	v_pk_fma_f32 v[110:111], v[110:111], s[70:71], v[106:107] op_sel_hi:[1,0,1]
	v_min_f32_e32 v108, 0x41e6d4ca, v108
	v_pk_mul_f32 v[110:111], v[110:111], s[72:73] op_sel_hi:[1,0]
	v_exp_f32_e32 v119, v108
	v_min_f32_e32 v108, 0x41e6d4ca, v109
	v_exp_f32_e32 v118, v108
	v_min_f32_e32 v108, 0x41e6d4ca, v110
	v_exp_f32_e32 v109, v108
	v_min_f32_e32 v108, 0x41e6d4ca, v111
	v_exp_f32_e32 v108, v108
	v_pk_add_f32 v[110:111], v[118:119], 1.0 op_sel_hi:[1,0]
	v_pk_add_f32 v[108:109], v[108:109], 1.0 op_sel_hi:[1,0]
	v_mul_f32_e32 v118, v111, v110
	v_mul_f32_e32 v119, v109, v108
	s_nop 0
	v_mul_f32_e32 v122, v118, v119
	v_rcp_f32_e32 v123, v122
	s_nop 0
	v_mul_f32_e32 v118, v118, v123
	v_pk_mul_f32 v[108:109], v[108:109], v[118:119] op_sel_hi:[1,0]
	v_mul_f32_e32 v122, v119, v123
	v_pk_mul_f32 v[108:109], v[106:107], v[108:109]
	v_pk_mul_f32 v[110:111], v[110:111], v[122:123] op_sel_hi:[1,0]
	v_pk_mul_f32 v[118:119], v[102:103], v[108:109]
	v_mov_b32_e32 v108, 0
	v_mov_b32_e32 v109, 0
	v_pk_mul_f32 v[110:111], v[104:105], v[110:111]
	v_mov_b32_dpp v108, v116 row_ror:1 row_mask:0xf bank_mask:0xf
	v_mov_b32_dpp v109, v117 row_ror:1 row_mask:0xf bank_mask:0xf
	v_pk_mul_f32 v[122:123], v[100:101], v[110:111]
	v_mov_b32_e32 v110, 0
	v_mov_b32_e32 v111, 0
	v_mov_b32_dpp v108, v128 row_shr:1 row_mask:0xf bank_mask:0xf
	v_mov_b32_dpp v109, v129 row_shr:1 row_mask:0xf bank_mask:0xf
	v_mov_b32_dpp v110, v114 row_ror:1 row_mask:0xf bank_mask:0xf
	v_mov_b32_dpp v111, v115 row_ror:1 row_mask:0xf bank_mask:0xf
	v_pk_fma_f32 v[108:109], v[64:65], v[108:109], v[68:69]
	v_mov_b32_dpp v110, v130 row_shr:1 row_mask:0xf bank_mask:0xf
	v_mov_b32_dpp v111, v131 row_shr:1 row_mask:0xf bank_mask:0xf
	v_pk_fma_f32 v[108:109], v[128:129], v[60:61], v[108:109]
	v_pk_fma_f32 v[110:111], v[66:67], v[110:111], v[70:71]
	v_pk_fma_f32 v[108:109], v[56:57], v[152:153], v[108:109]
	v_pk_fma_f32 v[110:111], v[130:131], v[62:63], v[110:111]
	v_pk_mul_f32 v[114:115], v[108:109], v[108:109]
	v_pk_fma_f32 v[110:111], v[58:59], v[154:155], v[110:111]
	v_pk_mul_f32 v[114:115], v[108:109], v[114:115]
	v_pk_mul_f32 v[116:117], v[110:111], v[110:111]
	v_pk_fma_f32 v[114:115], v[114:115], s[70:71], v[108:109] op_sel_hi:[1,0,1]
	v_pk_mul_f32 v[116:117], v[110:111], v[116:117]
	v_pk_mul_f32 v[114:115], v[114:115], s[72:73] op_sel_hi:[1,0]
	v_pk_fma_f32 v[116:117], v[116:117], s[70:71], v[110:111] op_sel_hi:[1,0,1]
	v_min_f32_e32 v114, 0x41e6d4ca, v114
	v_pk_mul_f32 v[116:117], v[116:117], s[72:73] op_sel_hi:[1,0]
	v_exp_f32_e32 v125, v114
	v_min_f32_e32 v114, 0x41e6d4ca, v115
	v_exp_f32_e32 v124, v114
	v_min_f32_e32 v114, 0x41e6d4ca, v116
	v_exp_f32_e32 v115, v114
	v_min_f32_e32 v114, 0x41e6d4ca, v117
	v_exp_f32_e32 v114, v114
	v_pk_add_f32 v[116:117], v[124:125], 1.0 op_sel_hi:[1,0]
	v_pk_add_f32 v[114:115], v[114:115], 1.0 op_sel_hi:[1,0]
	v_mul_f32_e32 v124, v117, v116
	v_mul_f32_e32 v125, v115, v114
	s_nop 0
	v_mul_f32_e32 v126, v124, v125
	v_rcp_f32_e32 v127, v126
	s_nop 0
	v_mul_f32_e32 v126, v125, v127
	v_mul_f32_e32 v124, v124, v127
	v_pk_mul_f32 v[114:115], v[114:115], v[124:125] op_sel_hi:[1,0]
	v_pk_mul_f32 v[116:117], v[116:117], v[126:127] op_sel_hi:[1,0]
	v_pk_mul_f32 v[114:115], v[110:111], v[114:115]
	v_pk_mul_f32 v[116:117], v[108:109], v[116:117]
	v_pk_mul_f32 v[124:125], v[98:99], v[114:115]
	v_pk_mul_f32 v[116:117], v[96:97], v[116:117]
	v_cvt_pk_bf16_f32 v115, v118, v119
	v_mad_i64_i32 v[118:119], s[10:11], v136, s90, v[120:121]
	v_cvt_pk_bf16_f32 v114, v122, v123
	v_cvt_pk_bf16_f32 v116, v116, v117
	v_cvt_pk_bf16_f32 v117, v124, v125
	v_lshl_add_u64 v[118:119], v[118:119], 0, v[112:113]
	global_store_dwordx4 v[118:119], v[114:117], off
	s_and_saveexec_b64 s[10:11], s[58:59]
	s_cbranch_execz .LBB0_772
	s_add_u32 s24, s4, s14
	s_addc_u32 s25, s5, s12
	v_lshl_add_u64 v[114:115], v[192:193], 2, s[24:25]
	global_store_dwordx4 v[114:115], v[104:107], off
	s_nop 1
	v_add_co_u32_e32 v104, vcc, 0x2000, v114
	s_nop 1
	v_addc_co_u32_e32 v105, vcc, 0, v115, vcc
	v_add_co_u32_e32 v106, vcc, 0x5000, v114
	global_store_dwordx4 v[104:105], v[132:135], off offset:3072
	s_nop 0
	v_addc_co_u32_e32 v107, vcc, 0, v115, vcc
	global_store_dwordx4 v[106:107], v[100:103], off offset:2048
	global_store_dwordx4 v[114:115], v[108:111], off offset:16
	global_store_dwordx4 v[104:105], v[128:131], off offset:3088
	global_store_dwordx4 v[106:107], v[96:99], off offset:2064

.LBB0_780:
	v_pk_mul_f32 v[116:117], v[52:53], v[198:199] op_sel_hi:[1,0]
	v_mov_b32_e32 v52, 0
	v_mov_b32_e32 v53, 0
	s_waitcnt lgkmcnt(0)
	v_mov_b32_dpp v108, v92 row_shr:1 row_mask:0xf bank_mask:0xf
	v_mov_b32_dpp v109, v93 row_shr:1 row_mask:0xf bank_mask:0xf
	v_mov_b32_dpp v52, v116 row_ror:15 row_mask:0xf bank_mask:0xf
	v_mov_b32_dpp v53, v117 row_ror:15 row_mask:0xf bank_mask:0xf
	v_pk_fma_f32 v[108:109], v[80:81], v[108:109], v[84:85]
	v_pk_mul_f32 v[114:115], v[54:55], v[198:199] op_sel_hi:[1,0]
	v_mov_b32_e32 v54, 0
	v_mov_b32_e32 v55, 0
	v_mov_b32_dpp v110, v94 row_shr:1 row_mask:0xf bank_mask:0xf
	v_mov_b32_dpp v111, v95 row_shr:1 row_mask:0xf bank_mask:0xf
	v_mov_b32_dpp v52, v92 row_shl:1 row_mask:0xf bank_mask:0xf
	v_mov_b32_dpp v53, v93 row_shl:1 row_mask:0xf bank_mask:0xf
	v_pk_fma_f32 v[108:109], v[92:93], v[76:77], v[108:109]
	v_mov_b32_dpp v54, v114 row_ror:15 row_mask:0xf bank_mask:0xf
	v_mov_b32_dpp v55, v115 row_ror:15 row_mask:0xf bank_mask:0xf
	v_pk_fma_f32 v[110:111], v[82:83], v[110:111], v[86:87]
	v_pk_fma_f32 v[52:53], v[72:73], v[52:53], v[108:109]
	v_mov_b32_dpp v54, v94 row_shl:1 row_mask:0xf bank_mask:0xf
	v_mov_b32_dpp v55, v95 row_shl:1 row_mask:0xf bank_mask:0xf
	v_pk_fma_f32 v[110:111], v[94:95], v[78:79], v[110:111]
	v_pk_mul_f32 v[108:109], v[52:53], v[52:53]
	v_pk_fma_f32 v[54:55], v[74:75], v[54:55], v[110:111]
	v_pk_mul_f32 v[108:109], v[52:53], v[108:109]
	v_pk_mul_f32 v[110:111], v[54:55], v[54:55]
	v_pk_fma_f32 v[108:109], v[108:109], s[70:71], v[52:53] op_sel_hi:[1,0,1]
	v_pk_mul_f32 v[110:111], v[54:55], v[110:111]
	v_pk_mul_f32 v[108:109], v[108:109], s[72:73] op_sel_hi:[1,0]
	v_pk_fma_f32 v[110:111], v[110:111], s[70:71], v[54:55] op_sel_hi:[1,0,1]
	v_min_f32_e32 v108, 0x41e6d4ca, v108
	v_pk_mul_f32 v[110:111], v[110:111], s[72:73] op_sel_hi:[1,0]
	v_exp_f32_e32 v121, v108
	v_min_f32_e32 v108, 0x41e6d4ca, v109
	v_exp_f32_e32 v120, v108
	v_min_f32_e32 v108, 0x41e6d4ca, v110
	v_exp_f32_e32 v109, v108
	v_min_f32_e32 v108, 0x41e6d4ca, v111
	v_exp_f32_e32 v108, v108
	v_mov_b32_e32 v118, v200
	v_mov_b32_e32 v119, v200
	v_pk_mul_f32 v[50:51], v[50:51], v[118:119]
	v_pk_mul_f32 v[42:43], v[42:43], v[118:119]
	v_pk_add_f32 v[118:119], v[120:121], 1.0 op_sel_hi:[1,0]
	v_pk_add_f32 v[120:121], v[108:109], 1.0 op_sel_hi:[1,0]
	v_mul_f32_e32 v122, v119, v118
	v_mul_f32_e32 v123, v121, v120
	v_pk_mul_f32 v[110:111], v[44:45], v[198:199] op_sel_hi:[1,0]
	v_mul_f32_e32 v108, v122, v123
	v_rcp_f32_e32 v125, v108
	v_mov_b32_dpp v104, v88 row_shr:1 row_mask:0xf bank_mask:0xf
	v_mov_b32_dpp v105, v89 row_shr:1 row_mask:0xf bank_mask:0xf
	v_pk_fma_f32 v[104:105], v[64:65], v[104:105], v[68:69]
	v_mul_f32_e32 v44, v122, v125
	v_pk_mul_f32 v[120:121], v[120:121], v[44:45] op_sel_hi:[1,0]
	v_mov_b32_e32 v44, 0
	v_mov_b32_e32 v45, 0
	v_pk_mul_f32 v[108:109], v[46:47], v[198:199] op_sel_hi:[1,0]
	v_mov_b32_dpp v44, v110 row_ror:15 row_mask:0xf bank_mask:0xf
	v_mov_b32_dpp v45, v111 row_ror:15 row_mask:0xf bank_mask:0xf
	v_mov_b32_e32 v46, 0
	v_mov_b32_e32 v47, 0
	v_mov_b32_dpp v106, v90 row_shr:1 row_mask:0xf bank_mask:0xf
	v_mov_b32_dpp v107, v91 row_shr:1 row_mask:0xf bank_mask:0xf
	v_mov_b32_dpp v44, v88 row_shl:1 row_mask:0xf bank_mask:0xf
	v_mov_b32_dpp v45, v89 row_shl:1 row_mask:0xf bank_mask:0xf
	v_pk_fma_f32 v[104:105], v[88:89], v[60:61], v[104:105]
	v_mov_b32_dpp v46, v108 row_ror:15 row_mask:0xf bank_mask:0xf
	v_mov_b32_dpp v47, v109 row_ror:15 row_mask:0xf bank_mask:0xf
	v_pk_fma_f32 v[106:107], v[66:67], v[106:107], v[70:71]
	v_pk_fma_f32 v[44:45], v[56:57], v[44:45], v[104:105]
	v_mov_b32_dpp v46, v90 row_shl:1 row_mask:0xf bank_mask:0xf
	v_mov_b32_dpp v47, v91 row_shl:1 row_mask:0xf bank_mask:0xf
	v_pk_fma_f32 v[106:107], v[90:91], v[62:63], v[106:107]
	v_pk_mul_f32 v[104:105], v[44:45], v[44:45]
	v_pk_fma_f32 v[46:47], v[58:59], v[46:47], v[106:107]
	v_pk_mul_f32 v[104:105], v[44:45], v[104:105]
	v_pk_mul_f32 v[106:107], v[46:47], v[46:47]
	v_pk_fma_f32 v[104:105], v[104:105], s[70:71], v[44:45] op_sel_hi:[1,0,1]
	v_pk_mul_f32 v[106:107], v[46:47], v[106:107]
	v_pk_mul_f32 v[104:105], v[104:105], s[72:73] op_sel_hi:[1,0]
	v_pk_fma_f32 v[106:107], v[106:107], s[70:71], v[46:47] op_sel_hi:[1,0,1]
	v_min_f32_e32 v104, 0x41e6d4ca, v104
	v_mul_f32_e32 v124, v123, v125
	v_pk_mul_f32 v[106:107], v[106:107], s[72:73] op_sel_hi:[1,0]
	v_exp_f32_e32 v123, v104
	v_min_f32_e32 v104, 0x41e6d4ca, v105
	v_exp_f32_e32 v122, v104
	v_min_f32_e32 v104, 0x41e6d4ca, v106
	v_exp_f32_e32 v105, v104
	v_min_f32_e32 v104, 0x41e6d4ca, v107
	v_exp_f32_e32 v104, v104
	v_pk_mul_f32 v[106:107], v[118:119], v[124:125] op_sel_hi:[1,0]
	v_pk_add_f32 v[118:119], v[122:123], 1.0 op_sel_hi:[1,0]
	v_pk_mul_f32 v[48:49], v[48:49], v[200:201]
	v_pk_add_f32 v[104:105], v[104:105], 1.0 op_sel_hi:[1,0]
	v_mul_f32_e32 v122, v119, v118
	v_mul_f32_e32 v123, v105, v104
	v_pk_mul_f32 v[40:41], v[40:41], v[200:201]
	v_mul_f32_e32 v124, v122, v123
	v_rcp_f32_e32 v125, v124
	v_pk_mul_f32 v[106:107], v[52:53], v[106:107]
	v_add_u32_e32 v126, 0x80, v197
	v_pk_mul_f32 v[106:107], v[48:49], v[106:107]
	v_mul_f32_e32 v124, v123, v125
	v_mul_f32_e32 v122, v122, v125
	v_pk_mul_f32 v[118:119], v[118:119], v[124:125] op_sel_hi:[1,0]
	v_pk_mul_f32 v[104:105], v[104:105], v[122:123] op_sel_hi:[1,0]
	v_pk_mul_f32 v[118:119], v[44:45], v[118:119]
	v_pk_mul_f32 v[104:105], v[46:47], v[104:105]
	v_pk_mul_f32 v[118:119], v[40:41], v[118:119]
	v_pk_mul_f32 v[120:121], v[54:55], v[120:121]
	v_pk_mul_f32 v[122:123], v[42:43], v[104:105]
	v_cvt_pk_bf16_f32 v104, v106, v107
	v_cvt_pk_bf16_f32 v106, v118, v119
	v_mov_b64_e32 v[118:119], s[86:87]
	v_pk_mul_f32 v[120:121], v[50:51], v[120:121]
	v_mad_i64_i32 v[118:119], s[10:11], v126, s90, v[118:119]
	v_cvt_pk_bf16_f32 v105, v120, v121
	v_cvt_pk_bf16_f32 v107, v122, v123
	v_lshl_add_u64 v[118:119], v[192:193], 1, v[118:119]
	global_store_dwordx4 v[118:119], v[104:107], off
	s_and_saveexec_b64 s[10:11], s[42:43]
	s_cbranch_execz .LBB0_782
	s_add_u32 s24, s4, s15
	s_addc_u32 s25, s5, s16
	v_lshl_add_u64 v[104:105], v[192:193], 2, s[24:25]
	global_store_dwordx4 v[104:105], v[52:55], off
	s_nop 1
	v_add_co_u32_e32 v52, vcc, 0x2000, v104
	s_nop 1
	v_addc_co_u32_e32 v53, vcc, 0, v105, vcc
	v_add_co_u32_e32 v54, vcc, 0x5000, v104
	global_store_dwordx4 v[52:53], v[92:95], off offset:3072
	s_nop 0
	v_addc_co_u32_e32 v55, vcc, 0, v105, vcc
	global_store_dwordx4 v[54:55], v[48:51], off offset:2048
	global_store_dwordx4 v[104:105], v[44:47], off offset:16
	global_store_dwordx4 v[52:53], v[88:91], off offset:3088
	global_store_dwordx4 v[54:55], v[40:43], off offset:2064
.LBB0_782:
	s_or_b64 exec, exec, s[10:11]
	s_nop 0
	v_mov_b32_e32 v40, v198
	v_mov_b32_e32 v41, v198
	v_pk_mul_f32 v[44:45], v[22:23], v[40:41]
	v_pk_mul_f32 v[40:41], v[18:19], v[40:41]
	v_pk_mul_f32 v[18:19], v[24:25], v[196:197] op_sel_hi:[1,0]
	v_mov_b32_e32 v24, v194
	v_mov_b32_e32 v25, v194
	v_pk_mul_f32 v[6:7], v[6:7], v[24:25]
	v_pk_mul_f32 v[2:3], v[2:3], v[24:25]
	v_mov_b32_e32 v24, 0
	v_mov_b32_e32 v25, 0
	v_mov_b32_e32 v199, v198
	v_mov_b32_dpp v24, v92 row_ror:1 row_mask:0xf bank_mask:0xf
	v_mov_b32_dpp v25, v93 row_ror:1 row_mask:0xf bank_mask:0xf
	v_pk_mul_f32 v[42:43], v[16:17], v[198:199]
	v_pk_mul_f32 v[22:23], v[28:29], v[196:197] op_sel_hi:[1,0]
	v_pk_mul_f32 v[16:17], v[26:27], v[196:197] op_sel_hi:[1,0]
	v_mov_b32_e32 v26, 0
	v_mov_b32_e32 v27, 0
	v_mov_b32_e32 v28, 0
	v_mov_b32_e32 v29, 0
	v_mov_b32_dpp v24, v116 row_shr:1 row_mask:0xf bank_mask:0xf
	v_mov_b32_dpp v25, v117 row_shr:1 row_mask:0xf bank_mask:0xf
	v_mov_b32_dpp v26, v94 row_ror:1 row_mask:0xf bank_mask:0xf
	v_mov_b32_dpp v27, v95 row_ror:1 row_mask:0xf bank_mask:0xf
	v_mov_b32_dpp v28, v22 row_ror:15 row_mask:0xf bank_mask:0xf
	v_mov_b32_dpp v29, v23 row_ror:15 row_mask:0xf bank_mask:0xf
	v_pk_fma_f32 v[24:25], v[80:81], v[24:25], v[84:85]
	v_pk_mul_f32 v[46:47], v[20:21], v[198:199]
	v_pk_mul_f32 v[20:21], v[30:31], v[196:197] op_sel_hi:[1,0]
	v_mov_b32_e32 v30, 0
	v_mov_b32_e32 v31, 0
	v_mov_b32_dpp v26, v114 row_shr:1 row_mask:0xf bank_mask:0xf
	v_mov_b32_dpp v27, v115 row_shr:1 row_mask:0xf bank_mask:0xf
	v_mov_b32_dpp v28, v116 row_shl:1 row_mask:0xf bank_mask:0xf
	v_mov_b32_dpp v29, v117 row_shl:1 row_mask:0xf bank_mask:0xf
	v_pk_fma_f32 v[24:25], v[116:117], v[76:77], v[24:25]
	v_mov_b32_dpp v30, v20 row_ror:15 row_mask:0xf bank_mask:0xf
	v_mov_b32_dpp v31, v21 row_ror:15 row_mask:0xf bank_mask:0xf
	v_pk_fma_f32 v[26:27], v[82:83], v[26:27], v[86:87]
	v_pk_fma_f32 v[24:25], v[72:73], v[28:29], v[24:25]
	v_mov_b32_dpp v30, v114 row_shl:1 row_mask:0xf bank_mask:0xf
	v_mov_b32_dpp v31, v115 row_shl:1 row_mask:0xf bank_mask:0xf
	v_pk_fma_f32 v[26:27], v[114:115], v[78:79], v[26:27]
	v_pk_mul_f32 v[28:29], v[24:25], v[24:25]
	v_pk_fma_f32 v[26:27], v[74:75], v[30:31], v[26:27]
	v_pk_mul_f32 v[28:29], v[24:25], v[28:29]
	v_pk_mul_f32 v[30:31], v[26:27], v[26:27]
	v_pk_fma_f32 v[28:29], v[28:29], s[70:71], v[24:25] op_sel_hi:[1,0,1]
	v_pk_mul_f32 v[30:31], v[26:27], v[30:31]
	v_pk_mul_f32 v[28:29], v[28:29], s[72:73] op_sel_hi:[1,0]
	v_pk_fma_f32 v[30:31], v[30:31], s[70:71], v[26:27] op_sel_hi:[1,0,1]
	v_min_f32_e32 v28, 0x41e6d4ca, v28
	v_pk_mul_f32 v[30:31], v[30:31], s[72:73] op_sel_hi:[1,0]
	v_exp_f32_e32 v49, v28
	v_min_f32_e32 v28, 0x41e6d4ca, v29
	v_exp_f32_e32 v48, v28
	v_min_f32_e32 v28, 0x41e6d4ca, v30
	v_exp_f32_e32 v29, v28
	v_min_f32_e32 v28, 0x41e6d4ca, v31
	v_exp_f32_e32 v28, v28
	v_pk_add_f32 v[30:31], v[48:49], 1.0 op_sel_hi:[1,0]
	v_add_u32_e32 v52, 0x90, v197
	v_pk_add_f32 v[28:29], v[28:29], 1.0 op_sel_hi:[1,0]
	v_mul_f32_e32 v48, v31, v30
	v_mul_f32_e32 v49, v29, v28
	v_pk_mul_f32 v[12:13], v[12:13], v[196:197] op_sel_hi:[1,0]
	v_mul_f32_e32 v50, v48, v49
	v_rcp_f32_e32 v51, v50
	v_pk_mul_f32 v[14:15], v[14:15], v[196:197] op_sel_hi:[1,0]
	v_pk_mul_f32 v[10:11], v[10:11], v[196:197] op_sel_hi:[1,0]
	v_pk_mul_f32 v[8:9], v[8:9], v[196:197] op_sel_hi:[1,0]
	v_mul_f32_e32 v48, v48, v51
	v_pk_mul_f32 v[28:29], v[28:29], v[48:49] op_sel_hi:[1,0]
	v_mul_f32_e32 v50, v49, v51
	v_pk_mul_f32 v[26:27], v[26:27], v[28:29]
	v_pk_mul_f32 v[30:31], v[30:31], v[50:51] op_sel_hi:[1,0]
	v_pk_mul_f32 v[28:29], v[44:45], v[26:27]
	v_mov_b32_e32 v26, 0
	v_mov_b32_e32 v27, 0
	v_pk_mul_f32 v[24:25], v[24:25], v[30:31]
	v_mov_b32_dpp v26, v88 row_ror:1 row_mask:0xf bank_mask:0xf
	v_mov_b32_dpp v27, v89 row_ror:1 row_mask:0xf bank_mask:0xf
	v_mov_b32_e32 v30, 0
	v_mov_b32_e32 v31, 0
	v_mov_b32_e32 v44, 0
	v_mov_b32_e32 v45, 0
	v_mov_b32_dpp v26, v110 row_shr:1 row_mask:0xf bank_mask:0xf
	v_mov_b32_dpp v27, v111 row_shr:1 row_mask:0xf bank_mask:0xf
	v_mov_b32_dpp v30, v90 row_ror:1 row_mask:0xf bank_mask:0xf
	v_mov_b32_dpp v31, v91 row_ror:1 row_mask:0xf bank_mask:0xf
	v_mov_b32_dpp v44, v18 row_ror:15 row_mask:0xf bank_mask:0xf
	v_mov_b32_dpp v45, v19 row_ror:15 row_mask:0xf bank_mask:0xf
	v_pk_fma_f32 v[26:27], v[64:65], v[26:27], v[68:69]
	v_pk_mul_f32 v[24:25], v[46:47], v[24:25]
	v_mov_b32_e32 v46, 0
	v_mov_b32_e32 v47, 0
	v_mov_b32_dpp v30, v108 row_shr:1 row_mask:0xf bank_mask:0xf
	v_mov_b32_dpp v31, v109 row_shr:1 row_mask:0xf bank_mask:0xf
	v_mov_b32_dpp v44, v110 row_shl:1 row_mask:0xf bank_mask:0xf
	v_mov_b32_dpp v45, v111 row_shl:1 row_mask:0xf bank_mask:0xf
	v_pk_fma_f32 v[26:27], v[110:111], v[60:61], v[26:27]
	v_mov_b32_dpp v46, v16 row_ror:15 row_mask:0xf bank_mask:0xf
	v_mov_b32_dpp v47, v17 row_ror:15 row_mask:0xf bank_mask:0xf
	v_pk_fma_f32 v[30:31], v[66:67], v[30:31], v[70:71]
	v_pk_fma_f32 v[26:27], v[56:57], v[44:45], v[26:27]
	v_mov_b32_dpp v46, v108 row_shl:1 row_mask:0xf bank_mask:0xf
	v_mov_b32_dpp v47, v109 row_shl:1 row_mask:0xf bank_mask:0xf
	v_pk_fma_f32 v[30:31], v[108:109], v[62:63], v[30:31]
	v_pk_mul_f32 v[44:45], v[26:27], v[26:27]
	v_pk_fma_f32 v[30:31], v[58:59], v[46:47], v[30:31]
	v_pk_mul_f32 v[44:45], v[26:27], v[44:45]
	v_pk_mul_f32 v[46:47], v[30:31], v[30:31]
	v_pk_fma_f32 v[44:45], v[44:45], s[70:71], v[26:27] op_sel_hi:[1,0,1]
	v_pk_mul_f32 v[46:47], v[30:31], v[46:47]
	v_pk_mul_f32 v[44:45], v[44:45], s[72:73] op_sel_hi:[1,0]
	v_pk_fma_f32 v[46:47], v[46:47], s[70:71], v[30:31] op_sel_hi:[1,0,1]
	v_min_f32_e32 v44, 0x41e6d4ca, v44
	v_pk_mul_f32 v[46:47], v[46:47], s[72:73] op_sel_hi:[1,0]
	v_exp_f32_e32 v49, v44
	v_min_f32_e32 v44, 0x41e6d4ca, v45
	v_exp_f32_e32 v48, v44
	v_min_f32_e32 v44, 0x41e6d4ca, v46
	v_exp_f32_e32 v45, v44
	v_min_f32_e32 v44, 0x41e6d4ca, v47
	v_exp_f32_e32 v44, v44
	v_pk_add_f32 v[46:47], v[48:49], 1.0 op_sel_hi:[1,0]
	v_mov_b32_dpp v100, v36 row_shl:1 row_mask:0xf bank_mask:0xf
	v_pk_add_f32 v[44:45], v[44:45], 1.0 op_sel_hi:[1,0]
	v_mul_f32_e32 v48, v47, v46
	v_mul_f32_e32 v49, v45, v44
	v_mov_b32_dpp v101, v37 row_shl:1 row_mask:0xf bank_mask:0xf
	v_mul_f32_e32 v50, v48, v49
	v_rcp_f32_e32 v51, v50
	v_mov_b32_dpp v102, v38 row_shl:1 row_mask:0xf bank_mask:0xf
	v_mov_b32_dpp v103, v39 row_shl:1 row_mask:0xf bank_mask:0xf
	v_pk_mul_f32 v[4:5], v[4:5], v[194:195]
	v_mul_f32_e32 v50, v49, v51
	v_mul_f32_e32 v48, v48, v51
	v_pk_mul_f32 v[44:45], v[44:45], v[48:49] op_sel_hi:[1,0]
	v_pk_mul_f32 v[46:47], v[46:47], v[50:51] op_sel_hi:[1,0]
	v_pk_mul_f32 v[30:31], v[30:31], v[44:45]
	v_pk_mul_f32 v[26:27], v[26:27], v[46:47]
	v_pk_mul_f32 v[30:31], v[40:41], v[30:31]
	v_pk_mul_f32 v[40:41], v[42:43], v[26:27]
	v_cvt_pk_bf16_f32 v26, v24, v25
	v_mov_b64_e32 v[24:25], s[86:87]
	v_cvt_pk_bf16_f32 v27, v28, v29
	v_cvt_pk_bf16_f32 v29, v30, v31
	v_mad_i64_i32 v[30:31], s[10:11], v52, s90, v[24:25]
	v_cvt_pk_bf16_f32 v28, v40, v41
	v_lshl_add_u64 v[30:31], v[30:31], 0, v[112:113]
	global_store_dwordx4 v[30:31], v[26:29], off
	v_mov_b32_e32 v30, 0
	v_mov_b32_e32 v31, 0
	v_mov_b32_e32 v26, 0
	v_mov_b32_e32 v27, 0
	v_mov_b32_e32 v28, 0
	v_mov_b32_dpp v26, v116 row_ror:1 row_mask:0xf bank_mask:0xf
	v_mov_b32_dpp v27, v117 row_ror:1 row_mask:0xf bank_mask:0xf
	v_mov_b32_e32 v29, 0
	v_mov_b32_dpp v26, v22 row_shr:1 row_mask:0xf bank_mask:0xf
	v_mov_b32_dpp v27, v23 row_shr:1 row_mask:0xf bank_mask:0xf
	v_mov_b32_dpp v28, v114 row_ror:1 row_mask:0xf bank_mask:0xf
	v_mov_b32_dpp v29, v115 row_ror:1 row_mask:0xf bank_mask:0xf
	v_mov_b32_dpp v30, v36 row_ror:15 row_mask:0xf bank_mask:0xf
	v_mov_b32_dpp v31, v37 row_ror:15 row_mask:0xf bank_mask:0xf
	v_pk_fma_f32 v[26:27], v[80:81], v[26:27], v[84:85]
	v_mov_b32_e32 v40, 0
	v_mov_b32_e32 v41, 0
	v_mov_b32_dpp v28, v20 row_shr:1 row_mask:0xf bank_mask:0xf
	v_mov_b32_dpp v29, v21 row_shr:1 row_mask:0xf bank_mask:0xf
	v_mov_b32_dpp v30, v22 row_shl:1 row_mask:0xf bank_mask:0xf
	v_mov_b32_dpp v31, v23 row_shl:1 row_mask:0xf bank_mask:0xf
	v_pk_fma_f32 v[26:27], v[22:23], v[76:77], v[26:27]
	v_mov_b32_dpp v40, v38 row_ror:15 row_mask:0xf bank_mask:0xf
	v_mov_b32_dpp v41, v39 row_ror:15 row_mask:0xf bank_mask:0xf
	v_pk_fma_f32 v[28:29], v[82:83], v[28:29], v[86:87]
	v_pk_fma_f32 v[26:27], v[72:73], v[30:31], v[26:27]
	v_mov_b32_dpp v40, v20 row_shl:1 row_mask:0xf bank_mask:0xf
	v_mov_b32_dpp v41, v21 row_shl:1 row_mask:0xf bank_mask:0xf
	v_pk_fma_f32 v[28:29], v[20:21], v[78:79], v[28:29]
	v_pk_mul_f32 v[30:31], v[26:27], v[26:27]
	v_pk_fma_f32 v[28:29], v[74:75], v[40:41], v[28:29]
	v_pk_mul_f32 v[30:31], v[26:27], v[30:31]
	v_pk_mul_f32 v[40:41], v[28:29], v[28:29]
	v_pk_fma_f32 v[30:31], v[30:31], s[70:71], v[26:27] op_sel_hi:[1,0,1]
	v_pk_mul_f32 v[40:41], v[28:29], v[40:41]
	v_pk_mul_f32 v[30:31], v[30:31], s[72:73] op_sel_hi:[1,0]
	v_pk_fma_f32 v[40:41], v[40:41], s[70:71], v[28:29] op_sel_hi:[1,0,1]
	v_min_f32_e32 v30, 0x41e6d4ca, v30
	v_pk_mul_f32 v[40:41], v[40:41], s[72:73] op_sel_hi:[1,0]
	v_exp_f32_e32 v43, v30
	v_min_f32_e32 v30, 0x41e6d4ca, v31
	v_exp_f32_e32 v42, v30
	v_min_f32_e32 v30, 0x41e6d4ca, v40
	v_exp_f32_e32 v31, v30
	v_min_f32_e32 v30, 0x41e6d4ca, v41
	v_exp_f32_e32 v30, v30
	v_pk_add_f32 v[40:41], v[42:43], 1.0 op_sel_hi:[1,0]
	v_add_u32_e32 v46, 0xa0, v197
	v_pk_add_f32 v[30:31], v[30:31], 1.0 op_sel_hi:[1,0]
	v_mul_f32_e32 v42, v41, v40
	v_mul_f32_e32 v43, v31, v30
	v_mov_b32_dpp v96, v32 row_shl:1 row_mask:0xf bank_mask:0xf
	v_mul_f32_e32 v44, v42, v43
	v_rcp_f32_e32 v45, v44
	v_mov_b32_dpp v97, v33 row_shl:1 row_mask:0xf bank_mask:0xf
	v_mov_b32_dpp v98, v34 row_shl:1 row_mask:0xf bank_mask:0xf
	v_mov_b32_dpp v99, v35 row_shl:1 row_mask:0xf bank_mask:0xf
	v_mul_f32_e32 v44, v43, v45
	v_pk_mul_f32 v[40:41], v[40:41], v[44:45] op_sel_hi:[1,0]
	v_mul_f32_e32 v42, v42, v45
	v_pk_mul_f32 v[26:27], v[26:27], v[40:41]
	v_pk_mul_f32 v[30:31], v[30:31], v[42:43] op_sel_hi:[1,0]
	v_pk_mul_f32 v[12:13], v[12:13], v[26:27]
	v_mov_b32_e32 v26, 0
	v_mov_b32_e32 v27, 0
	v_pk_mul_f32 v[28:29], v[28:29], v[30:31]
	v_mov_b32_dpp v26, v110 row_ror:1 row_mask:0xf bank_mask:0xf
	v_mov_b32_dpp v27, v111 row_ror:1 row_mask:0xf bank_mask:0xf
	v_pk_mul_f32 v[14:15], v[14:15], v[28:29]
	v_mov_b32_e32 v28, 0
	v_mov_b32_e32 v29, 0
	v_mov_b32_e32 v30, 0
	v_mov_b32_e32 v31, 0
	v_mov_b32_dpp v26, v18 row_shr:1 row_mask:0xf bank_mask:0xf
	v_mov_b32_dpp v27, v19 row_shr:1 row_mask:0xf bank_mask:0xf
	v_mov_b32_dpp v28, v108 row_ror:1 row_mask:0xf bank_mask:0xf
	v_mov_b32_dpp v29, v109 row_ror:1 row_mask:0xf bank_mask:0xf
	v_mov_b32_dpp v30, v32 row_ror:15 row_mask:0xf bank_mask:0xf
	v_mov_b32_dpp v31, v33 row_ror:15 row_mask:0xf bank_mask:0xf
	v_pk_fma_f32 v[26:27], v[64:65], v[26:27], v[68:69]
	v_mov_b32_e32 v40, 0
	v_mov_b32_e32 v41, 0
	v_mov_b32_dpp v28, v16 row_shr:1 row_mask:0xf bank_mask:0xf
	v_mov_b32_dpp v29, v17 row_shr:1 row_mask:0xf bank_mask:0xf
	v_mov_b32_dpp v30, v18 row_shl:1 row_mask:0xf bank_mask:0xf
	v_mov_b32_dpp v31, v19 row_shl:1 row_mask:0xf bank_mask:0xf
	v_pk_fma_f32 v[26:27], v[18:19], v[60:61], v[26:27]
	v_mov_b32_dpp v40, v34 row_ror:15 row_mask:0xf bank_mask:0xf
	v_mov_b32_dpp v41, v35 row_ror:15 row_mask:0xf bank_mask:0xf
	v_pk_fma_f32 v[28:29], v[66:67], v[28:29], v[70:71]
	v_pk_fma_f32 v[26:27], v[56:57], v[30:31], v[26:27]
	v_mov_b32_dpp v40, v16 row_shl:1 row_mask:0xf bank_mask:0xf
	v_mov_b32_dpp v41, v17 row_shl:1 row_mask:0xf bank_mask:0xf
	v_pk_fma_f32 v[28:29], v[16:17], v[62:63], v[28:29]
	v_pk_mul_f32 v[30:31], v[26:27], v[26:27]
	v_pk_fma_f32 v[28:29], v[58:59], v[40:41], v[28:29]
	v_pk_mul_f32 v[30:31], v[26:27], v[30:31]
	v_pk_mul_f32 v[40:41], v[28:29], v[28:29]
	v_pk_fma_f32 v[30:31], v[30:31], s[70:71], v[26:27] op_sel_hi:[1,0,1]
	v_pk_mul_f32 v[40:41], v[28:29], v[40:41]
	v_pk_mul_f32 v[30:31], v[30:31], s[72:73] op_sel_hi:[1,0]
	v_pk_fma_f32 v[40:41], v[40:41], s[70:71], v[28:29] op_sel_hi:[1,0,1]
	v_min_f32_e32 v30, 0x41e6d4ca, v30
	v_pk_mul_f32 v[40:41], v[40:41], s[72:73] op_sel_hi:[1,0]
	v_exp_f32_e32 v43, v30
	v_min_f32_e32 v30, 0x41e6d4ca, v31
	v_exp_f32_e32 v42, v30
	v_min_f32_e32 v30, 0x41e6d4ca, v40
	v_exp_f32_e32 v31, v30
	v_min_f32_e32 v30, 0x41e6d4ca, v41
	v_exp_f32_e32 v30, v30
	v_pk_add_f32 v[40:41], v[42:43], 1.0 op_sel_hi:[1,0]
	v_pk_mul_f32 v[0:1], v[0:1], v[194:195]
	v_pk_add_f32 v[30:31], v[30:31], 1.0 op_sel_hi:[1,0]
	v_mul_f32_e32 v42, v41, v40
	v_mul_f32_e32 v43, v31, v30
	s_nop 0
	v_mul_f32_e32 v44, v42, v43
	v_rcp_f32_e32 v45, v44
	s_nop 0
	v_mul_f32_e32 v44, v43, v45
	v_mul_f32_e32 v42, v42, v45
	v_pk_mul_f32 v[30:31], v[30:31], v[42:43] op_sel_hi:[1,0]
	v_pk_mul_f32 v[40:41], v[40:41], v[44:45] op_sel_hi:[1,0]
	v_pk_mul_f32 v[28:29], v[28:29], v[30:31]
	v_pk_mul_f32 v[26:27], v[26:27], v[40:41]
	v_pk_mul_f32 v[28:29], v[10:11], v[28:29]
	v_pk_mul_f32 v[10:11], v[8:9], v[26:27]
	v_cvt_pk_bf16_f32 v8, v12, v13
	v_mad_i64_i32 v[12:13], s[10:11], v46, s90, v[24:25]
	v_cvt_pk_bf16_f32 v9, v14, v15
	v_cvt_pk_bf16_f32 v10, v10, v11
	v_cvt_pk_bf16_f32 v11, v28, v29
	v_lshl_add_u64 v[12:13], v[12:13], 0, v[112:113]
	global_store_dwordx4 v[12:13], v[8:11], off
	v_add_u32_e32 v30, 0xb0, v197
	s_nop 0
	v_mov_b32_e32 v8, 0
	v_mov_b32_e32 v9, 0
	v_mov_b32_e32 v10, 0
	v_mov_b32_dpp v8, v22 row_ror:1 row_mask:0xf bank_mask:0xf
	v_mov_b32_dpp v9, v23 row_ror:1 row_mask:0xf bank_mask:0xf
	v_mov_b32_e32 v11, 0
	v_mov_b32_dpp v8, v36 row_shr:1 row_mask:0xf bank_mask:0xf
	v_mov_b32_dpp v9, v37 row_shr:1 row_mask:0xf bank_mask:0xf
	v_mov_b32_dpp v10, v20 row_ror:1 row_mask:0xf bank_mask:0xf
	v_mov_b32_dpp v11, v21 row_ror:1 row_mask:0xf bank_mask:0xf
	v_pk_fma_f32 v[8:9], v[80:81], v[8:9], v[84:85]
	v_mov_b32_dpp v10, v38 row_shr:1 row_mask:0xf bank_mask:0xf
	v_mov_b32_dpp v11, v39 row_shr:1 row_mask:0xf bank_mask:0xf
	v_pk_fma_f32 v[8:9], v[36:37], v[76:77], v[8:9]
	v_pk_fma_f32 v[10:11], v[82:83], v[10:11], v[86:87]
	v_pk_fma_f32 v[8:9], v[72:73], v[100:101], v[8:9]
	v_pk_fma_f32 v[10:11], v[38:39], v[78:79], v[10:11]
	v_pk_mul_f32 v[12:13], v[8:9], v[8:9]
	v_pk_fma_f32 v[10:11], v[74:75], v[102:103], v[10:11]
	v_pk_mul_f32 v[12:13], v[8:9], v[12:13]
	v_pk_mul_f32 v[14:15], v[10:11], v[10:11]
	v_pk_fma_f32 v[12:13], v[12:13], s[70:71], v[8:9] op_sel_hi:[1,0,1]
	v_pk_mul_f32 v[14:15], v[10:11], v[14:15]
	v_pk_mul_f32 v[12:13], v[12:13], s[72:73] op_sel_hi:[1,0]
	v_pk_fma_f32 v[14:15], v[14:15], s[70:71], v[10:11] op_sel_hi:[1,0,1]
	v_min_f32_e32 v12, 0x41e6d4ca, v12
	v_pk_mul_f32 v[14:15], v[14:15], s[72:73] op_sel_hi:[1,0]
	v_exp_f32_e32 v21, v12
	v_min_f32_e32 v12, 0x41e6d4ca, v13
	v_exp_f32_e32 v20, v12
	v_min_f32_e32 v12, 0x41e6d4ca, v14
	v_exp_f32_e32 v13, v12
	v_min_f32_e32 v12, 0x41e6d4ca, v15
	v_exp_f32_e32 v12, v12
	v_pk_add_f32 v[14:15], v[20:21], 1.0 op_sel_hi:[1,0]
	v_pk_add_f32 v[12:13], v[12:13], 1.0 op_sel_hi:[1,0]
	v_mul_f32_e32 v20, v15, v14
	v_mul_f32_e32 v21, v13, v12
	s_nop 0
	v_mul_f32_e32 v22, v20, v21
	v_rcp_f32_e32 v23, v22
	s_nop 0
	v_mul_f32_e32 v20, v20, v23
	v_pk_mul_f32 v[12:13], v[12:13], v[20:21] op_sel_hi:[1,0]
	v_mul_f32_e32 v22, v21, v23
	v_pk_mul_f32 v[12:13], v[10:11], v[12:13]
	v_pk_mul_f32 v[14:15], v[14:15], v[22:23] op_sel_hi:[1,0]
	v_pk_mul_f32 v[20:21], v[6:7], v[12:13]
	v_mov_b32_e32 v12, 0
	v_mov_b32_e32 v13, 0
	v_pk_mul_f32 v[14:15], v[8:9], v[14:15]
	v_mov_b32_dpp v12, v18 row_ror:1 row_mask:0xf bank_mask:0xf
	v_mov_b32_dpp v13, v19 row_ror:1 row_mask:0xf bank_mask:0xf
	v_pk_mul_f32 v[22:23], v[4:5], v[14:15]
	v_mov_b32_e32 v14, 0
	v_mov_b32_e32 v15, 0
	v_mov_b32_dpp v12, v32 row_shr:1 row_mask:0xf bank_mask:0xf
	v_mov_b32_dpp v13, v33 row_shr:1 row_mask:0xf bank_mask:0xf
	v_mov_b32_dpp v14, v16 row_ror:1 row_mask:0xf bank_mask:0xf
	v_mov_b32_dpp v15, v17 row_ror:1 row_mask:0xf bank_mask:0xf
	v_pk_fma_f32 v[12:13], v[64:65], v[12:13], v[68:69]
	v_mov_b32_dpp v14, v34 row_shr:1 row_mask:0xf bank_mask:0xf
	v_mov_b32_dpp v15, v35 row_shr:1 row_mask:0xf bank_mask:0xf
	v_pk_fma_f32 v[12:13], v[32:33], v[60:61], v[12:13]
	v_pk_fma_f32 v[14:15], v[66:67], v[14:15], v[70:71]
	v_pk_fma_f32 v[12:13], v[56:57], v[96:97], v[12:13]
	v_pk_fma_f32 v[14:15], v[34:35], v[62:63], v[14:15]
	v_pk_mul_f32 v[16:17], v[12:13], v[12:13]
	v_pk_fma_f32 v[14:15], v[58:59], v[98:99], v[14:15]
	v_pk_mul_f32 v[16:17], v[12:13], v[16:17]
	v_pk_mul_f32 v[18:19], v[14:15], v[14:15]
	v_pk_fma_f32 v[16:17], v[16:17], s[70:71], v[12:13] op_sel_hi:[1,0,1]
	v_pk_mul_f32 v[18:19], v[14:15], v[18:19]
	v_pk_mul_f32 v[16:17], v[16:17], s[72:73] op_sel_hi:[1,0]
	v_pk_fma_f32 v[18:19], v[18:19], s[70:71], v[14:15] op_sel_hi:[1,0,1]
	v_min_f32_e32 v16, 0x41e6d4ca, v16
	v_pk_mul_f32 v[18:19], v[18:19], s[72:73] op_sel_hi:[1,0]
	v_exp_f32_e32 v27, v16
	v_min_f32_e32 v16, 0x41e6d4ca, v17
	v_exp_f32_e32 v26, v16
	v_min_f32_e32 v16, 0x41e6d4ca, v18
	v_exp_f32_e32 v17, v16
	v_min_f32_e32 v16, 0x41e6d4ca, v19
	v_exp_f32_e32 v16, v16
	v_pk_add_f32 v[18:19], v[26:27], 1.0 op_sel_hi:[1,0]
	v_pk_add_f32 v[16:17], v[16:17], 1.0 op_sel_hi:[1,0]
	v_mul_f32_e32 v26, v19, v18
	v_mul_f32_e32 v27, v17, v16
	s_nop 0
	v_mul_f32_e32 v28, v26, v27
	v_rcp_f32_e32 v29, v28
	s_nop 0
	v_mul_f32_e32 v28, v27, v29
	v_mul_f32_e32 v26, v26, v29
	v_pk_mul_f32 v[16:17], v[16:17], v[26:27] op_sel_hi:[1,0]
	v_pk_mul_f32 v[18:19], v[18:19], v[28:29] op_sel_hi:[1,0]
	v_pk_mul_f32 v[16:17], v[14:15], v[16:17]
	v_pk_mul_f32 v[18:19], v[12:13], v[18:19]
	v_pk_mul_f32 v[26:27], v[2:3], v[16:17]
	v_pk_mul_f32 v[18:19], v[0:1], v[18:19]
	v_cvt_pk_bf16_f32 v17, v20, v21
	v_mad_i64_i32 v[20:21], s[10:11], v30, s90, v[24:25]
	v_cvt_pk_bf16_f32 v16, v22, v23
	v_cvt_pk_bf16_f32 v18, v18, v19
	v_cvt_pk_bf16_f32 v19, v26, v27
	v_lshl_add_u64 v[20:21], v[20:21], 0, v[112:113]
	global_store_dwordx4 v[20:21], v[16:19], off
	s_and_saveexec_b64 s[10:11], s[64:65]
	s_cbranch_execz .LBB0_784
	s_add_u32 s14, s4, s14
	s_addc_u32 s15, s5, s12
	v_lshl_add_u64 v[16:17], v[192:193], 2, s[14:15]
	global_store_dwordx4 v[16:17], v[8:11], off
	s_nop 1
	v_add_co_u32_e32 v8, vcc, 0x2000, v16
	s_nop 1
	v_addc_co_u32_e32 v9, vcc, 0, v17, vcc
	v_add_co_u32_e32 v10, vcc, 0x5000, v16
	global_store_dwordx4 v[8:9], v[36:39], off offset:3072
	s_nop 0
	v_addc_co_u32_e32 v11, vcc, 0, v17, vcc
	global_store_dwordx4 v[10:11], v[4:7], off offset:2048
	global_store_dwordx4 v[16:17], v[12:15], off offset:16
	global_store_dwordx4 v[8:9], v[32:35], off offset:3088
	global_store_dwordx4 v[10:11], v[0:3], off offset:2064
